# GEMM main loops: drop the s_setprio 0/1 flip in the middle of each 32-MFMA block (wave keeps priority through the block)
# speedup vs baseline: 1.0038x; 1.0038x over previous
; #define PG8_STAGE(bufoff, gbase, voff) do { _Pragma("unroll") for (int _i = 0; _i < 2; ++_i) \
;         __builtin_amdgcn_global_load_lds((const unsigned*)((const char*)(gbase) + (voff)[_i]), (PG8_LAS unsigned*)(lds + (bufoff) + ldsw + _i * 8192), 16, 0, 0); } while (0)
; #define PG8_LDA(dst, b, h) do { _Pragma("unroll") for (int m = 0; m < 4; ++m) _Pragma("unroll") for (int k = 0; k < 2; ++k) dst[m][k] = *(const PG8_LAS bf16x8*)(lds + PG8_SA(b, h) + aoff + m * 2048 + k * 1024); } while (0)
; #define PG8_LDB(dst, b, h) do { _Pragma("unroll") for (int n = 0; n < 2; ++n) _Pragma("unroll") for (int k = 0; k < 2; ++k) dst[n][k] = *(const PG8_LAS bf16x8*)(lds + PG8_SB(b, h) + boff + n * 2048 + k * 1024); } while (0)
; #define PG8_MMA(ai, bj, At, Bt) do { __builtin_amdgcn_s_setprio(1); _Pragma("unroll") for (int m = 0; m < 4; ++m) _Pragma("unroll") for (int n = 0; n < 2; ++n) _Pragma("unroll") for (int k = 0; k < 2; ++k) \
;         acc[ai][bj][m][n] = __builtin_amdgcn_mfma_f32_16x16x32_bf16(Bt[n][k], At[m][k], acc[ai][bj][m][n], 0, 0, 0); __builtin_amdgcn_s_setprio(0); } while (0)
; #define PG8_WAIT_V(n) asm volatile("s_waitcnt vmcnt(" #n ")" ::: "memory")
; #define PG8_WAIT_L(n) asm volatile("s_waitcnt lgkmcnt(" #n ")" ::: "memory")
; template <class Epi, class Sched, bool ALIGN_EPI = false, bool SP2 = false>
; __device__ __forceinline__ void gemm_phase(PG8_LAS unsigned char* lds, const Gemm g, const Sched& S, const Epi& E) {
;     ...
;             const bool last = (t == nt - 2);
;             const char* a1 = cA + (size_t)(t + 1) * kstep;
;             const char* a2 = last ? nA : cA + (size_t)(t + 2) * kstep; const char* b2 = last ? nB : cB + (size_t)(t + 2) * kstep;
;             const char* a3 = a2 + kstep; const char* b3 = b2 + kstep;
;             if (last && has_next) S.a_ready(nxt);
;             if constexpr (SP2) {
;             PG8_LDB(B0, 0, 0); PG8_LDB(B1, 0, 1); PG8_SCHED; PG8_LDA(At, 0, 0); PG8_STAGE(PG8_SA(1, 1), a1 + hstep, voffA);
;             PG8_WAIT_V(8); PG8_WAIT_L(0); PG8_BAR; PG8_MMA(0, 0, At, B0); PG8_MMA(0, 1, At, B1); PG8_BAR; PG8_SCHED;
;             PG8_LDA(At, 0, 1); PG8_STAGE(PG8_SB(0, 0), b2, voffB); PG8_STAGE(PG8_SB(0, 1), b2 + hstep, voffB); PG8_STAGE(PG8_SA(0, 0), a2, voffA);
;             PG8_WAIT_V(8); PG8_WAIT_L(0); PG8_BAR; PG8_MMA(1, 0, At, B0); PG8_MMA(1, 1, At, B1); PG8_BAR; PG8_SCHED;
.LBB0_219:
	s_add_u32 s46, s38, 0xfffc0080
	s_addc_u32 s47, s39, -1
	s_add_i32 s56, 0, 0x10000
	s_cmp_eq_u32 vcc_lo, 12
	s_cselect_b32 s49, s50, s47
	s_cselect_b32 s48, s51, s46
	s_cselect_b32 s47, s52, s73
	s_cselect_b32 s46, s53, s71
	s_add_i32 vcc_hi, 0, 0x14000
	v_add_u32_e32 v152, s56, v165
	v_add_u32_e32 v169, vcc_hi, v165
	ds_read_b128 v[128:131], v152
	ds_read_b128 v[144:147], v152 offset:1024
	ds_read_b128 v[148:151], v152 offset:2048
	ds_read_b128 v[152:155], v152 offset:3072
	ds_read_b128 v[156:159], v169
	ds_read_b128 v[160:163], v169 offset:1024
	ds_read_b128 v[170:173], v169 offset:2048
	ds_read_b128 v[180:183], v169 offset:3072
	v_lshl_add_u64 v[176:177], s[38:39], 0, v[140:141]
	s_add_i32 m0, s9, 0xc000
	ds_read_b128 v[184:187], v168
	ds_read_b128 v[188:191], v168 offset:1024
	ds_read_b128 v[192:195], v168 offset:2048
	ds_read_b128 v[196:199], v168 offset:3072
	ds_read_b128 v[200:203], v168 offset:4096
	ds_read_b128 v[204:207], v168 offset:5120
	ds_read_b128 v[218:221], v168 offset:6144
	ds_read_b128 v[222:225], v168 offset:7168
	global_load_lds_dwordx4 v[176:177], off
	v_lshl_add_u64 v[176:177], s[38:39], 0, v[142:143]
	s_add_i32 m0, s9, 0xe000
	s_nop 0
	global_load_lds_dwordx4 v[176:177], off
	s_waitcnt vmcnt(8)
	s_waitcnt lgkmcnt(0)
	s_barrier
	s_setprio 1
	s_waitcnt lgkmcnt(0)
	v_mfma_f32_16x16x32_bf16 v[124:127], v[128:131], v[184:187], v[124:127]
	v_mfma_f32_16x16x32_bf16 v[120:123], v[148:151], v[184:187], v[120:123]
	v_mfma_f32_16x16x32_bf16 v[108:111], v[128:131], v[192:195], v[108:111]
	v_mfma_f32_16x16x32_bf16 v[104:107], v[148:151], v[192:195], v[104:107]
	v_mfma_f32_16x16x32_bf16 v[92:95], v[128:131], v[200:203], v[92:95]
	v_mfma_f32_16x16x32_bf16 v[88:91], v[148:151], v[200:203], v[88:91]
	v_mfma_f32_16x16x32_bf16 v[76:79], v[128:131], v[218:221], v[76:79]
	v_mfma_f32_16x16x32_bf16 v[72:75], v[148:151], v[218:221], v[72:75]
	v_mfma_f32_16x16x32_bf16 v[124:127], v[144:147], v[188:191], v[124:127]
	v_mfma_f32_16x16x32_bf16 v[120:123], v[152:155], v[188:191], v[120:123]
	v_mfma_f32_16x16x32_bf16 v[108:111], v[144:147], v[196:199], v[108:111]
	v_mfma_f32_16x16x32_bf16 v[104:107], v[152:155], v[196:199], v[104:107]
	v_mfma_f32_16x16x32_bf16 v[92:95], v[144:147], v[204:207], v[92:95]
	v_mfma_f32_16x16x32_bf16 v[88:91], v[152:155], v[204:207], v[88:91]
	v_mfma_f32_16x16x32_bf16 v[76:79], v[144:147], v[222:225], v[76:79]
	v_mfma_f32_16x16x32_bf16 v[72:75], v[152:155], v[222:225], v[72:75]
	v_mfma_f32_16x16x32_bf16 v[116:119], v[156:159], v[184:187], v[116:119]
	v_mfma_f32_16x16x32_bf16 v[112:115], v[170:173], v[184:187], v[112:115]
	v_mfma_f32_16x16x32_bf16 v[100:103], v[156:159], v[192:195], v[100:103]
	v_mfma_f32_16x16x32_bf16 v[96:99], v[170:173], v[192:195], v[96:99]
	v_mfma_f32_16x16x32_bf16 v[84:87], v[156:159], v[200:203], v[84:87]
	v_mfma_f32_16x16x32_bf16 v[80:83], v[170:173], v[200:203], v[80:83]
	v_mfma_f32_16x16x32_bf16 v[68:71], v[156:159], v[218:221], v[68:71]
	v_mfma_f32_16x16x32_bf16 v[64:67], v[170:173], v[218:221], v[64:67]
	v_mfma_f32_16x16x32_bf16 v[116:119], v[160:163], v[188:191], v[116:119]
	v_mfma_f32_16x16x32_bf16 v[112:115], v[180:183], v[188:191], v[112:115]
	v_mfma_f32_16x16x32_bf16 v[100:103], v[160:163], v[196:199], v[100:103]
	v_mfma_f32_16x16x32_bf16 v[96:99], v[180:183], v[196:199], v[96:99]
	v_mfma_f32_16x16x32_bf16 v[84:87], v[160:163], v[204:207], v[84:87]
	v_mfma_f32_16x16x32_bf16 v[80:83], v[180:183], v[204:207], v[80:83]
	v_mfma_f32_16x16x32_bf16 v[68:71], v[160:163], v[222:225], v[68:71]
	v_mfma_f32_16x16x32_bf16 v[64:67], v[180:183], v[222:225], v[64:67]
	s_setprio 0
	s_barrier
	s_add_i32 s56, s56, s8
	v_lshl_add_u64 v[176:177], s[46:47], 0, v[174:175]
	s_mov_b32 m0, s56
	ds_read_b128 v[184:187], v168 offset:16384
	ds_read_b128 v[188:191], v168 offset:17408
	ds_read_b128 v[192:195], v168 offset:18432
	ds_read_b128 v[196:199], v168 offset:19456
	ds_read_b128 v[200:203], v168 offset:20480
	ds_read_b128 v[204:207], v168 offset:21504
	ds_read_b128 v[218:221], v168 offset:22528
	ds_read_b128 v[222:225], v168 offset:23552
	global_load_lds_dwordx4 v[176:177], off
	s_add_i32 m0, s56, 0x2000
	s_add_u32 s56, s46, 0x40000
	v_lshl_add_u64 v[178:179], s[46:47], 0, v[136:137]
	s_addc_u32 s57, s47, 0
	s_add_i32 vcc_hi, vcc_hi, s8
	global_load_lds_dwordx4 v[178:179], off
	v_lshl_add_u64 v[208:209], s[56:57], 0, v[174:175]
	s_mov_b32 m0, vcc_hi
	v_lshl_add_u64 v[226:227], s[48:49], 0, v[134:135]
	global_load_lds_dwordx4 v[208:209], off
	v_lshl_add_u64 v[208:209], s[56:57], 0, v[136:137]
	s_add_i32 m0, vcc_hi, 0x2000
	s_nop 0
	global_load_lds_dwordx4 v[208:209], off
	v_lshl_add_u64 v[208:209], s[48:49], 0, v[132:133]
	s_mov_b32 m0, s9
	s_nop 0
	global_load_lds_dwordx4 v[208:209], off
	s_mov_b32 m0, s79
	s_nop 0
	global_load_lds_dwordx4 v[226:227], off
	s_waitcnt vmcnt(8)
	s_waitcnt lgkmcnt(0)
	s_barrier
; #define PG8_STAGE(bufoff, gbase, voff) do { _Pragma("unroll") for (int _i = 0; _i < 2; ++_i) \
;         __builtin_amdgcn_global_load_lds((const unsigned*)((const char*)(gbase) + (voff)[_i]), (PG8_LAS unsigned*)(lds + (bufoff) + ldsw + _i * 8192), 16, 0, 0); } while (0)
; #define PG8_LDA(dst, b, h) do { _Pragma("unroll") for (int m = 0; m < 4; ++m) _Pragma("unroll") for (int k = 0; k < 2; ++k) dst[m][k] = *(const PG8_LAS bf16x8*)(lds + PG8_SA(b, h) + aoff + m * 2048 + k * 1024); } while (0)
; #define PG8_LDB(dst, b, h) do { _Pragma("unroll") for (int n = 0; n < 2; ++n) _Pragma("unroll") for (int k = 0; k < 2; ++k) dst[n][k] = *(const PG8_LAS bf16x8*)(lds + PG8_SB(b, h) + boff + n * 2048 + k * 1024); } while (0)
; #define PG8_MMA(ai, bj, At, Bt) do { __builtin_amdgcn_s_setprio(1); _Pragma("unroll") for (int m = 0; m < 4; ++m) _Pragma("unroll") for (int n = 0; n < 2; ++n) _Pragma("unroll") for (int k = 0; k < 2; ++k) \
;         acc[ai][bj][m][n] = __builtin_amdgcn_mfma_f32_16x16x32_bf16(Bt[n][k], At[m][k], acc[ai][bj][m][n], 0, 0, 0); __builtin_amdgcn_s_setprio(0); } while (0)
; #define PG8_WAIT_V(n) asm volatile("s_waitcnt vmcnt(" #n ")" ::: "memory")
; #define PG8_WAIT_L(n) asm volatile("s_waitcnt lgkmcnt(" #n ")" ::: "memory")
; #define PG8_BAR __builtin_amdgcn_s_barrier()
; #define PG8_SCHED __builtin_amdgcn_sched_barrier(0)
; template <class Epi, class Sched, bool ALIGN_EPI = false, bool SP2 = false>
; __device__ __forceinline__ void gemm_phase(PG8_LAS unsigned char* lds, const Gemm g, const Sched& S, const Epi& E) {
;     ...
;             PG8_WAIT_V(8); PG8_WAIT_L(0); PG8_BAR; PG8_MMA(1, 0, At, B0); PG8_MMA(1, 1, At, B1); PG8_BAR; PG8_SCHED;
;             PG8_LDB(B0, 1, 0); PG8_LDB(B1, 1, 1); PG8_SCHED; PG8_LDA(At, 1, 0); PG8_STAGE(PG8_SA(0, 1), a2 + hstep, voffA);
;             PG8_WAIT_V(8); PG8_WAIT_L(0); PG8_BAR; PG8_MMA(0, 0, At, B0); PG8_MMA(0, 1, At, B1); PG8_BAR; PG8_SCHED;
;             PG8_LDA(At, 1, 1); PG8_STAGE(PG8_SB(1, 0), b3, voffB); PG8_STAGE(PG8_SB(1, 1), b3 + hstep, voffB); PG8_STAGE(PG8_SA(1, 0), a3, voffA);
	s_setprio 1
	s_waitcnt lgkmcnt(0)
	v_mfma_f32_16x16x32_bf16 v[60:63], v[128:131], v[184:187], v[60:63]
	v_mfma_f32_16x16x32_bf16 v[56:59], v[148:151], v[184:187], v[56:59]
	v_mfma_f32_16x16x32_bf16 v[44:47], v[128:131], v[192:195], v[44:47]
	v_mfma_f32_16x16x32_bf16 v[40:43], v[148:151], v[192:195], v[40:43]
	v_mfma_f32_16x16x32_bf16 v[28:31], v[128:131], v[200:203], v[28:31]
	v_mfma_f32_16x16x32_bf16 v[24:27], v[148:151], v[200:203], v[24:27]
	v_mfma_f32_16x16x32_bf16 v[12:15], v[128:131], v[218:221], v[12:15]
	v_mfma_f32_16x16x32_bf16 v[8:11], v[148:151], v[218:221], v[8:11]
	v_mfma_f32_16x16x32_bf16 v[60:63], v[144:147], v[188:191], v[60:63]
	v_mfma_f32_16x16x32_bf16 v[56:59], v[152:155], v[188:191], v[56:59]
	v_mfma_f32_16x16x32_bf16 v[44:47], v[144:147], v[196:199], v[44:47]
	v_mfma_f32_16x16x32_bf16 v[40:43], v[152:155], v[196:199], v[40:43]
	v_mfma_f32_16x16x32_bf16 v[28:31], v[144:147], v[204:207], v[28:31]
	v_mfma_f32_16x16x32_bf16 v[24:27], v[152:155], v[204:207], v[24:27]
	v_mfma_f32_16x16x32_bf16 v[12:15], v[144:147], v[222:225], v[12:15]
	v_mfma_f32_16x16x32_bf16 v[8:11], v[152:155], v[222:225], v[8:11]
	v_mfma_f32_16x16x32_bf16 v[52:55], v[156:159], v[184:187], v[52:55]
	v_mfma_f32_16x16x32_bf16 v[48:51], v[170:173], v[184:187], v[48:51]
	v_mfma_f32_16x16x32_bf16 v[36:39], v[156:159], v[192:195], v[36:39]
	v_mfma_f32_16x16x32_bf16 v[32:35], v[170:173], v[192:195], v[32:35]
	v_mfma_f32_16x16x32_bf16 v[20:23], v[156:159], v[200:203], v[20:23]
	v_mfma_f32_16x16x32_bf16 v[16:19], v[170:173], v[200:203], v[16:19]
	v_mfma_f32_16x16x32_bf16 v[4:7], v[156:159], v[218:221], v[4:7]
	v_mfma_f32_16x16x32_bf16 v[0:3], v[170:173], v[218:221], v[0:3]
	v_mfma_f32_16x16x32_bf16 v[52:55], v[160:163], v[188:191], v[52:55]
	v_mfma_f32_16x16x32_bf16 v[48:51], v[180:183], v[188:191], v[48:51]
	v_mfma_f32_16x16x32_bf16 v[36:39], v[160:163], v[196:199], v[36:39]
	v_mfma_f32_16x16x32_bf16 v[32:35], v[180:183], v[196:199], v[32:35]
	v_mfma_f32_16x16x32_bf16 v[20:23], v[160:163], v[204:207], v[20:23]
	v_mfma_f32_16x16x32_bf16 v[16:19], v[180:183], v[204:207], v[16:19]
	v_mfma_f32_16x16x32_bf16 v[4:7], v[160:163], v[222:225], v[4:7]
	v_mfma_f32_16x16x32_bf16 v[0:3], v[180:183], v[222:225], v[0:3]
	s_setprio 0
	s_barrier
	s_add_i32 s56, 0, 0x18000
	s_add_i32 s57, 0, 0x1c000
	v_add_u32_e32 v152, s56, v165
	v_add_u32_e32 v169, s57, v165
	ds_read_b128 v[128:131], v152
	ds_read_b128 v[144:147], v152 offset:1024
	ds_read_b128 v[148:151], v152 offset:2048
	ds_read_b128 v[152:155], v152 offset:3072
	ds_read_b128 v[156:159], v169
	ds_read_b128 v[160:163], v169 offset:1024
	ds_read_b128 v[170:173], v169 offset:2048
	ds_read_b128 v[180:183], v169 offset:3072
	s_add_u32 s48, s48, 0x40000
	s_addc_u32 s49, s49, 0
	s_mov_b32 m0, s54
	v_lshl_add_u64 v[228:229], s[48:49], 0, v[132:133]
	ds_read_b128 v[184:187], v168 offset:32768
	ds_read_b128 v[188:191], v168 offset:33792
	ds_read_b128 v[192:195], v168 offset:34816
	ds_read_b128 v[196:199], v168 offset:35840
	ds_read_b128 v[200:203], v168 offset:36864
	ds_read_b128 v[204:207], v168 offset:37888
	ds_read_b128 v[218:221], v168 offset:38912
	ds_read_b128 v[222:225], v168 offset:39936
	global_load_lds_dwordx4 v[228:229], off
	v_lshl_add_u64 v[228:229], s[48:49], 0, v[134:135]
	s_mov_b32 m0, s55
	s_nop 0
	global_load_lds_dwordx4 v[228:229], off
	s_waitcnt vmcnt(8)
	s_waitcnt lgkmcnt(0)
	s_barrier
	s_setprio 1
	s_waitcnt lgkmcnt(0)
	v_mfma_f32_16x16x32_bf16 v[124:127], v[128:131], v[184:187], v[124:127]
	v_mfma_f32_16x16x32_bf16 v[120:123], v[148:151], v[184:187], v[120:123]
	v_mfma_f32_16x16x32_bf16 v[108:111], v[128:131], v[192:195], v[108:111]
	v_mfma_f32_16x16x32_bf16 v[104:107], v[148:151], v[192:195], v[104:107]
	v_mfma_f32_16x16x32_bf16 v[92:95], v[128:131], v[200:203], v[92:95]
	v_mfma_f32_16x16x32_bf16 v[88:91], v[148:151], v[200:203], v[88:91]
	v_mfma_f32_16x16x32_bf16 v[76:79], v[128:131], v[218:221], v[76:79]
	v_mfma_f32_16x16x32_bf16 v[72:75], v[148:151], v[218:221], v[72:75]
	v_mfma_f32_16x16x32_bf16 v[124:127], v[144:147], v[188:191], v[124:127]
	v_mfma_f32_16x16x32_bf16 v[120:123], v[152:155], v[188:191], v[120:123]
	v_mfma_f32_16x16x32_bf16 v[108:111], v[144:147], v[196:199], v[108:111]
	v_mfma_f32_16x16x32_bf16 v[104:107], v[152:155], v[196:199], v[104:107]
	v_mfma_f32_16x16x32_bf16 v[92:95], v[144:147], v[204:207], v[92:95]
	v_mfma_f32_16x16x32_bf16 v[88:91], v[152:155], v[204:207], v[88:91]
	v_mfma_f32_16x16x32_bf16 v[76:79], v[144:147], v[222:225], v[76:79]
	v_mfma_f32_16x16x32_bf16 v[72:75], v[152:155], v[222:225], v[72:75]
	v_mfma_f32_16x16x32_bf16 v[116:119], v[156:159], v[184:187], v[116:119]
	v_mfma_f32_16x16x32_bf16 v[112:115], v[170:173], v[184:187], v[112:115]
	v_mfma_f32_16x16x32_bf16 v[100:103], v[156:159], v[192:195], v[100:103]
	v_mfma_f32_16x16x32_bf16 v[96:99], v[170:173], v[192:195], v[96:99]
	v_mfma_f32_16x16x32_bf16 v[84:87], v[156:159], v[200:203], v[84:87]
	v_mfma_f32_16x16x32_bf16 v[80:83], v[170:173], v[200:203], v[80:83]
	v_mfma_f32_16x16x32_bf16 v[68:71], v[156:159], v[218:221], v[68:71]
	v_mfma_f32_16x16x32_bf16 v[64:67], v[170:173], v[218:221], v[64:67]
	v_mfma_f32_16x16x32_bf16 v[116:119], v[160:163], v[188:191], v[116:119]
	v_mfma_f32_16x16x32_bf16 v[112:115], v[180:183], v[188:191], v[112:115]
	v_mfma_f32_16x16x32_bf16 v[100:103], v[160:163], v[196:199], v[100:103]
	v_mfma_f32_16x16x32_bf16 v[96:99], v[180:183], v[196:199], v[96:99]
	v_mfma_f32_16x16x32_bf16 v[84:87], v[160:163], v[204:207], v[84:87]
	v_mfma_f32_16x16x32_bf16 v[80:83], v[180:183], v[204:207], v[80:83]
	v_mfma_f32_16x16x32_bf16 v[68:71], v[160:163], v[222:225], v[68:71]
	v_mfma_f32_16x16x32_bf16 v[64:67], v[180:183], v[222:225], v[64:67]
	s_setprio 0
	s_barrier
; #define PG8_STAGE(bufoff, gbase, voff) do { _Pragma("unroll") for (int _i = 0; _i < 2; ++_i) \
;         __builtin_amdgcn_global_load_lds((const unsigned*)((const char*)(gbase) + (voff)[_i]), (PG8_LAS unsigned*)(lds + (bufoff) + ldsw + _i * 8192), 16, 0, 0); } while (0)
; #define PG8_LDA(dst, b, h) do { _Pragma("unroll") for (int m = 0; m < 4; ++m) _Pragma("unroll") for (int k = 0; k < 2; ++k) dst[m][k] = *(const PG8_LAS bf16x8*)(lds + PG8_SA(b, h) + aoff + m * 2048 + k * 1024); } while (0)
; #define PG8_MMA(ai, bj, At, Bt) do { __builtin_amdgcn_s_setprio(1); _Pragma("unroll") for (int m = 0; m < 4; ++m) _Pragma("unroll") for (int n = 0; n < 2; ++n) _Pragma("unroll") for (int k = 0; k < 2; ++k) \
;         acc[ai][bj][m][n] = __builtin_amdgcn_mfma_f32_16x16x32_bf16(Bt[n][k], At[m][k], acc[ai][bj][m][n], 0, 0, 0); __builtin_amdgcn_s_setprio(0); } while (0)
; #define PG8_WAIT_V(n) asm volatile("s_waitcnt vmcnt(" #n ")" ::: "memory")
; #define PG8_WAIT_L(n) asm volatile("s_waitcnt lgkmcnt(" #n ")" ::: "memory")
; #define PG8_BAR __builtin_amdgcn_s_barrier()
; #define PG8_SCHED __builtin_amdgcn_sched_barrier(0)
; template <class Epi, class Sched, bool ALIGN_EPI = false, bool SP2 = false>
; __device__ __forceinline__ void gemm_phase(PG8_LAS unsigned char* lds, const Gemm g, const Sched& S, const Epi& E) {
;     ...
;             PG8_LDA(At, 1, 1); PG8_STAGE(PG8_SB(1, 0), b3, voffB); PG8_STAGE(PG8_SB(1, 1), b3 + hstep, voffB); PG8_STAGE(PG8_SA(1, 0), a3, voffA);
;             PG8_WAIT_V(8); PG8_WAIT_L(0); PG8_BAR; PG8_MMA(1, 0, At, B0); PG8_MMA(1, 1, At, B1); PG8_BAR; PG8_SCHED;
;     ...
;         if constexpr (ALIGN_EPI) { if (wr == 0) PG8_BAR; }
	s_add_i32 s48, s56, s8
	v_lshl_add_u64 v[176:177], v[176:177], 0, s[4:5]
	s_mov_b32 m0, s48
	ds_read_b128 v[184:187], v168 offset:49152
	ds_read_b128 v[188:191], v168 offset:50176
	ds_read_b128 v[192:195], v168 offset:51200
	ds_read_b128 v[196:199], v168 offset:52224
	ds_read_b128 v[200:203], v168 offset:53248
	ds_read_b128 v[204:207], v168 offset:54272
	ds_read_b128 v[218:221], v168 offset:55296
	ds_read_b128 v[222:225], v168 offset:56320
	global_load_lds_dwordx4 v[176:177], off
	s_add_i32 m0, s48, 0x2000
	s_add_u32 s46, s46, 0x40080
	v_lshl_add_u64 v[176:177], v[178:179], 0, s[4:5]
	s_addc_u32 s47, s47, 0
	s_add_i32 s48, s57, s8
	global_load_lds_dwordx4 v[176:177], off
	v_lshl_add_u64 v[176:177], s[46:47], 0, v[174:175]
	s_mov_b32 m0, s48
	s_nop 0
	global_load_lds_dwordx4 v[176:177], off
	v_lshl_add_u64 v[176:177], s[46:47], 0, v[136:137]
	s_add_i32 m0, s48, 0x2000
	s_nop 0
	global_load_lds_dwordx4 v[176:177], off
	v_lshl_add_u64 v[176:177], v[208:209], 0, s[4:5]
	s_mov_b32 m0, s93
	s_nop 0
	global_load_lds_dwordx4 v[176:177], off
	v_lshl_add_u64 v[176:177], v[226:227], 0, s[4:5]
	s_mov_b32 m0, s66
	s_nop 0
	global_load_lds_dwordx4 v[176:177], off
	s_waitcnt vmcnt(8)
	s_waitcnt lgkmcnt(0)
	s_barrier
	s_setprio 1
	s_waitcnt lgkmcnt(0)
	v_mfma_f32_16x16x32_bf16 v[60:63], v[128:131], v[184:187], v[60:63]
	v_mfma_f32_16x16x32_bf16 v[56:59], v[148:151], v[184:187], v[56:59]
	v_mfma_f32_16x16x32_bf16 v[44:47], v[128:131], v[192:195], v[44:47]
	v_mfma_f32_16x16x32_bf16 v[40:43], v[148:151], v[192:195], v[40:43]
	v_mfma_f32_16x16x32_bf16 v[28:31], v[128:131], v[200:203], v[28:31]
	v_mfma_f32_16x16x32_bf16 v[24:27], v[148:151], v[200:203], v[24:27]
	v_mfma_f32_16x16x32_bf16 v[12:15], v[128:131], v[218:221], v[12:15]
	v_mfma_f32_16x16x32_bf16 v[8:11], v[148:151], v[218:221], v[8:11]
	v_mfma_f32_16x16x32_bf16 v[60:63], v[144:147], v[188:191], v[60:63]
	v_mfma_f32_16x16x32_bf16 v[56:59], v[152:155], v[188:191], v[56:59]
	v_mfma_f32_16x16x32_bf16 v[44:47], v[144:147], v[196:199], v[44:47]
	v_mfma_f32_16x16x32_bf16 v[40:43], v[152:155], v[196:199], v[40:43]
	v_mfma_f32_16x16x32_bf16 v[28:31], v[144:147], v[204:207], v[28:31]
	v_mfma_f32_16x16x32_bf16 v[24:27], v[152:155], v[204:207], v[24:27]
	v_mfma_f32_16x16x32_bf16 v[12:15], v[144:147], v[222:225], v[12:15]
	v_mfma_f32_16x16x32_bf16 v[8:11], v[152:155], v[222:225], v[8:11]
	v_mfma_f32_16x16x32_bf16 v[52:55], v[156:159], v[184:187], v[52:55]
	v_mfma_f32_16x16x32_bf16 v[48:51], v[170:173], v[184:187], v[48:51]
	v_mfma_f32_16x16x32_bf16 v[36:39], v[156:159], v[192:195], v[36:39]
	v_mfma_f32_16x16x32_bf16 v[32:35], v[170:173], v[192:195], v[32:35]
	v_mfma_f32_16x16x32_bf16 v[20:23], v[156:159], v[200:203], v[20:23]
	v_mfma_f32_16x16x32_bf16 v[16:19], v[170:173], v[200:203], v[16:19]
	v_mfma_f32_16x16x32_bf16 v[4:7], v[156:159], v[218:221], v[4:7]
	v_mfma_f32_16x16x32_bf16 v[0:3], v[170:173], v[218:221], v[0:3]
	v_mfma_f32_16x16x32_bf16 v[52:55], v[160:163], v[188:191], v[52:55]
	v_mfma_f32_16x16x32_bf16 v[48:51], v[180:183], v[188:191], v[48:51]
	v_mfma_f32_16x16x32_bf16 v[36:39], v[160:163], v[196:199], v[36:39]
	v_mfma_f32_16x16x32_bf16 v[32:35], v[180:183], v[196:199], v[32:35]
	v_mfma_f32_16x16x32_bf16 v[20:23], v[160:163], v[204:207], v[20:23]
	v_mfma_f32_16x16x32_bf16 v[16:19], v[180:183], v[204:207], v[16:19]
	v_mfma_f32_16x16x32_bf16 v[4:7], v[160:163], v[222:225], v[4:7]
	v_mfma_f32_16x16x32_bf16 v[0:3], v[180:183], v[222:225], v[0:3]
	s_setprio 0
	s_barrier
	s_add_i32 vcc_lo, vcc_lo, 2
	s_add_u32 s38, s38, 0x100
	s_addc_u32 s39, s39, 0
	s_add_u32 s71, s71, 0x100
	s_addc_u32 s73, s73, 0
	s_cmp_gt_u32 vcc_lo, 13
	s_cbranch_scc0 .LBB0_219
	s_and_b64 vcc, exec, s[68:69]
	s_cbranch_vccz .LBB0_222
	s_barrier

; #define PG8_STAGE(bufoff, gbase, voff) do { _Pragma("unroll") for (int _i = 0; _i < 2; ++_i) \
;         __builtin_amdgcn_global_load_lds((const unsigned*)((const char*)(gbase) + (voff)[_i]), (PG8_LAS unsigned*)(lds + (bufoff) + ldsw + _i * 8192), 16, 0, 0); } while (0)
; #define PG8_LDA(dst, b, h) do { _Pragma("unroll") for (int m = 0; m < 4; ++m) _Pragma("unroll") for (int k = 0; k < 2; ++k) dst[m][k] = *(const PG8_LAS bf16x8*)(lds + PG8_SA(b, h) + aoff + m * 2048 + k * 1024); } while (0)
; #define PG8_LDB(dst, b, h) do { _Pragma("unroll") for (int n = 0; n < 2; ++n) _Pragma("unroll") for (int k = 0; k < 2; ++k) dst[n][k] = *(const PG8_LAS bf16x8*)(lds + PG8_SB(b, h) + boff + n * 2048 + k * 1024); } while (0)
; #define PG8_MMA(ai, bj, At, Bt) do { __builtin_amdgcn_s_setprio(1); _Pragma("unroll") for (int m = 0; m < 4; ++m) _Pragma("unroll") for (int n = 0; n < 2; ++n) _Pragma("unroll") for (int k = 0; k < 2; ++k) \
;         acc[ai][bj][m][n] = __builtin_amdgcn_mfma_f32_16x16x32_bf16(Bt[n][k], At[m][k], acc[ai][bj][m][n], 0, 0, 0); __builtin_amdgcn_s_setprio(0); } while (0)
; #define PG8_WAIT_V(n) asm volatile("s_waitcnt vmcnt(" #n ")" ::: "memory")
; #define PG8_WAIT_L(n) asm volatile("s_waitcnt lgkmcnt(" #n ")" ::: "memory")
; template <class Epi, class Sched, bool ALIGN_EPI = false, bool SP2 = false>
; __device__ __forceinline__ void gemm_phase(PG8_LAS unsigned char* lds, const Gemm g, const Sched& S, const Epi& E) {
;     ...
;             const bool last = (t == nt - 2);
;             const char* a1 = cA + (size_t)(t + 1) * kstep;
;             const char* a2 = last ? nA : cA + (size_t)(t + 2) * kstep; const char* b2 = last ? nB : cB + (size_t)(t + 2) * kstep;
;             const char* a3 = a2 + kstep; const char* b3 = b2 + kstep;
;             if (last && has_next) S.a_ready(nxt);
;             if constexpr (SP2) {
;             PG8_LDB(B0, 0, 0); PG8_LDB(B1, 0, 1); PG8_SCHED; PG8_LDA(At, 0, 0); PG8_STAGE(PG8_SA(1, 1), a1 + hstep, voffA);
;             PG8_WAIT_V(8); PG8_WAIT_L(0); PG8_BAR; PG8_MMA(0, 0, At, B0); PG8_MMA(0, 1, At, B1); PG8_BAR; PG8_SCHED;
;             PG8_LDA(At, 0, 1); PG8_STAGE(PG8_SB(0, 0), b2, voffB); PG8_STAGE(PG8_SB(0, 1), b2 + hstep, voffB); PG8_STAGE(PG8_SA(0, 0), a2, voffA);
;             PG8_WAIT_V(8); PG8_WAIT_L(0); PG8_BAR; PG8_MMA(1, 0, At, B0); PG8_MMA(1, 1, At, B1); PG8_BAR; PG8_SCHED;
.LBB0_1641:
	s_add_i32 s78, s38, 2
	s_add_u32 s79, s0, 0x80
	s_addc_u32 s39, s1, 0
	s_add_i32 s93, 0, 0x10000
	s_cmp_eq_u32 s75, s38
	s_cselect_b32 s39, s63, s39
	s_cselect_b32 s38, s62, s79
	s_cselect_b32 s95, s65, s45
	s_cselect_b32 s94, s64, s44
	s_add_i32 s79, 0, 0x14000
	v_add_u32_e32 v68, s93, v218
	v_add_u32_e32 v156, s79, v218
	ds_read_b128 v[56:59], v68
	ds_read_b128 v[60:63], v68 offset:1024
	ds_read_b128 v[64:67], v68 offset:2048
	ds_read_b128 v[68:71], v68 offset:3072
	ds_read_b128 v[144:147], v156
	ds_read_b128 v[148:151], v156 offset:1024
	ds_read_b128 v[152:155], v156 offset:2048
	ds_read_b128 v[156:159], v156 offset:3072
	v_lshl_add_u64 v[172:173], s[0:1], 0, v[186:187]
	s_add_i32 m0, s9, 0xc000
	ds_read_b128 v[160:163], v220
	ds_read_b128 v[164:167], v220 offset:1024
	ds_read_b128 v[168:171], v220 offset:2048
	ds_read_b128 v[176:179], v220 offset:3072
	ds_read_b128 v[190:193], v220 offset:4096
	ds_read_b128 v[194:197], v220 offset:5120
	ds_read_b128 v[198:201], v220 offset:6144
	ds_read_b128 v[202:205], v220 offset:7168
	global_load_lds_dwordx4 v[172:173], off
	v_lshl_add_u64 v[172:173], s[0:1], 0, v[188:189]
	s_add_i32 m0, s9, 0xe000
	s_nop 0
	global_load_lds_dwordx4 v[172:173], off
	s_waitcnt vmcnt(8)
	s_waitcnt lgkmcnt(0)
	s_barrier
	s_setprio 1
	s_waitcnt lgkmcnt(0)
	v_mfma_f32_16x16x32_bf16 v[140:143], v[56:59], v[160:163], v[140:143]
	v_mfma_f32_16x16x32_bf16 v[136:139], v[64:67], v[160:163], v[136:139]
	v_mfma_f32_16x16x32_bf16 v[124:127], v[56:59], v[168:171], v[124:127]
	v_mfma_f32_16x16x32_bf16 v[120:123], v[64:67], v[168:171], v[120:123]
	v_mfma_f32_16x16x32_bf16 v[108:111], v[56:59], v[190:193], v[108:111]
	v_mfma_f32_16x16x32_bf16 v[104:107], v[64:67], v[190:193], v[104:107]
	v_mfma_f32_16x16x32_bf16 v[92:95], v[56:59], v[198:201], v[92:95]
	v_mfma_f32_16x16x32_bf16 v[88:91], v[64:67], v[198:201], v[88:91]
	v_mfma_f32_16x16x32_bf16 v[140:143], v[60:63], v[164:167], v[140:143]
	v_mfma_f32_16x16x32_bf16 v[136:139], v[68:71], v[164:167], v[136:139]
	v_mfma_f32_16x16x32_bf16 v[124:127], v[60:63], v[176:179], v[124:127]
	v_mfma_f32_16x16x32_bf16 v[120:123], v[68:71], v[176:179], v[120:123]
	v_mfma_f32_16x16x32_bf16 v[108:111], v[60:63], v[194:197], v[108:111]
	v_mfma_f32_16x16x32_bf16 v[104:107], v[68:71], v[194:197], v[104:107]
	v_mfma_f32_16x16x32_bf16 v[92:95], v[60:63], v[202:205], v[92:95]
	v_mfma_f32_16x16x32_bf16 v[88:91], v[68:71], v[202:205], v[88:91]
	v_mfma_f32_16x16x32_bf16 v[132:135], v[144:147], v[160:163], v[132:135]
	v_mfma_f32_16x16x32_bf16 v[128:131], v[152:155], v[160:163], v[128:131]
	v_mfma_f32_16x16x32_bf16 v[116:119], v[144:147], v[168:171], v[116:119]
	v_mfma_f32_16x16x32_bf16 v[112:115], v[152:155], v[168:171], v[112:115]
	v_mfma_f32_16x16x32_bf16 v[100:103], v[144:147], v[190:193], v[100:103]
	v_mfma_f32_16x16x32_bf16 v[96:99], v[152:155], v[190:193], v[96:99]
	v_mfma_f32_16x16x32_bf16 v[84:87], v[144:147], v[198:201], v[84:87]
	v_mfma_f32_16x16x32_bf16 v[80:83], v[152:155], v[198:201], v[80:83]
	v_mfma_f32_16x16x32_bf16 v[132:135], v[148:151], v[164:167], v[132:135]
	v_mfma_f32_16x16x32_bf16 v[128:131], v[156:159], v[164:167], v[128:131]
	v_mfma_f32_16x16x32_bf16 v[116:119], v[148:151], v[176:179], v[116:119]
	v_mfma_f32_16x16x32_bf16 v[112:115], v[156:159], v[176:179], v[112:115]
	v_mfma_f32_16x16x32_bf16 v[100:103], v[148:151], v[194:197], v[100:103]
	v_mfma_f32_16x16x32_bf16 v[96:99], v[156:159], v[194:197], v[96:99]
	v_mfma_f32_16x16x32_bf16 v[84:87], v[148:151], v[202:205], v[84:87]
	v_mfma_f32_16x16x32_bf16 v[80:83], v[156:159], v[202:205], v[80:83]
	s_setprio 0
	s_barrier
	s_add_i32 s93, s93, s8
	v_lshl_add_u64 v[172:173], s[94:95], 0, v[174:175]
	s_mov_b32 m0, s93
	ds_read_b128 v[160:163], v220 offset:16384
	ds_read_b128 v[164:167], v220 offset:17408
	ds_read_b128 v[168:171], v220 offset:18432
	ds_read_b128 v[176:179], v220 offset:19456
	ds_read_b128 v[190:193], v220 offset:20480
	ds_read_b128 v[194:197], v220 offset:21504
	ds_read_b128 v[198:201], v220 offset:22528
	ds_read_b128 v[202:205], v220 offset:23552
	global_load_lds_dwordx4 v[172:173], off
	s_add_i32 m0, s93, 0x2000
	v_lshl_add_u64 v[206:207], s[94:95], 0, v[180:181]
	s_add_u32 s94, s94, s50
	s_addc_u32 s95, s95, 0
	s_add_i32 s79, s79, s8
	global_load_lds_dwordx4 v[206:207], off
	v_lshl_add_u64 v[208:209], s[94:95], 0, v[174:175]
	s_mov_b32 m0, s79
	v_lshl_add_u64 v[222:223], s[94:95], 0, v[180:181]
	global_load_lds_dwordx4 v[208:209], off
	s_add_i32 m0, s79, 0x2000
	v_lshl_add_u64 v[224:225], s[38:39], 0, v[184:185]
	global_load_lds_dwordx4 v[222:223], off
	s_mov_b32 m0, s9
	v_lshl_add_u64 v[226:227], s[38:39], 0, v[182:183]
	global_load_lds_dwordx4 v[224:225], off
	s_mov_b32 m0, s67
	s_nop 0
	global_load_lds_dwordx4 v[226:227], off
	s_waitcnt vmcnt(8)
	s_waitcnt lgkmcnt(0)
	s_barrier
; #define PG8_STAGE(bufoff, gbase, voff) do { _Pragma("unroll") for (int _i = 0; _i < 2; ++_i) \
;         __builtin_amdgcn_global_load_lds((const unsigned*)((const char*)(gbase) + (voff)[_i]), (PG8_LAS unsigned*)(lds + (bufoff) + ldsw + _i * 8192), 16, 0, 0); } while (0)
; #define PG8_LDA(dst, b, h) do { _Pragma("unroll") for (int m = 0; m < 4; ++m) _Pragma("unroll") for (int k = 0; k < 2; ++k) dst[m][k] = *(const PG8_LAS bf16x8*)(lds + PG8_SA(b, h) + aoff + m * 2048 + k * 1024); } while (0)
; #define PG8_LDB(dst, b, h) do { _Pragma("unroll") for (int n = 0; n < 2; ++n) _Pragma("unroll") for (int k = 0; k < 2; ++k) dst[n][k] = *(const PG8_LAS bf16x8*)(lds + PG8_SB(b, h) + boff + n * 2048 + k * 1024); } while (0)
; #define PG8_MMA(ai, bj, At, Bt) do { __builtin_amdgcn_s_setprio(1); _Pragma("unroll") for (int m = 0; m < 4; ++m) _Pragma("unroll") for (int n = 0; n < 2; ++n) _Pragma("unroll") for (int k = 0; k < 2; ++k) \
;         acc[ai][bj][m][n] = __builtin_amdgcn_mfma_f32_16x16x32_bf16(Bt[n][k], At[m][k], acc[ai][bj][m][n], 0, 0, 0); __builtin_amdgcn_s_setprio(0); } while (0)
; #define PG8_WAIT_V(n) asm volatile("s_waitcnt vmcnt(" #n ")" ::: "memory")
; #define PG8_WAIT_L(n) asm volatile("s_waitcnt lgkmcnt(" #n ")" ::: "memory")
; #define PG8_BAR __builtin_amdgcn_s_barrier()
; #define PG8_SCHED __builtin_amdgcn_sched_barrier(0)
; template <class Epi, class Sched, bool ALIGN_EPI = false, bool SP2 = false>
; __device__ __forceinline__ void gemm_phase(PG8_LAS unsigned char* lds, const Gemm g, const Sched& S, const Epi& E) {
;     ...
;             PG8_WAIT_V(8); PG8_WAIT_L(0); PG8_BAR; PG8_MMA(1, 0, At, B0); PG8_MMA(1, 1, At, B1); PG8_BAR; PG8_SCHED;
;             PG8_LDB(B0, 1, 0); PG8_LDB(B1, 1, 1); PG8_SCHED; PG8_LDA(At, 1, 0); PG8_STAGE(PG8_SA(0, 1), a2 + hstep, voffA);
;             PG8_WAIT_V(8); PG8_WAIT_L(0); PG8_BAR; PG8_MMA(0, 0, At, B0); PG8_MMA(0, 1, At, B1); PG8_BAR; PG8_SCHED;
;             PG8_LDA(At, 1, 1); PG8_STAGE(PG8_SB(1, 0), b3, voffB); PG8_STAGE(PG8_SB(1, 1), b3 + hstep, voffB); PG8_STAGE(PG8_SA(1, 0), a3, voffA);
	s_setprio 1
	s_waitcnt lgkmcnt(0)
	v_mfma_f32_16x16x32_bf16 v[76:79], v[56:59], v[160:163], v[76:79]
	v_mfma_f32_16x16x32_bf16 v[72:75], v[64:67], v[160:163], v[72:75]
	v_mfma_f32_16x16x32_bf16 v[44:47], v[56:59], v[168:171], v[44:47]
	v_mfma_f32_16x16x32_bf16 v[40:43], v[64:67], v[168:171], v[40:43]
	v_mfma_f32_16x16x32_bf16 v[28:31], v[56:59], v[190:193], v[28:31]
	v_mfma_f32_16x16x32_bf16 v[24:27], v[64:67], v[190:193], v[24:27]
	v_mfma_f32_16x16x32_bf16 v[12:15], v[56:59], v[198:201], v[12:15]
	v_mfma_f32_16x16x32_bf16 v[8:11], v[64:67], v[198:201], v[8:11]
	v_mfma_f32_16x16x32_bf16 v[76:79], v[60:63], v[164:167], v[76:79]
	v_mfma_f32_16x16x32_bf16 v[72:75], v[68:71], v[164:167], v[72:75]
	v_mfma_f32_16x16x32_bf16 v[44:47], v[60:63], v[176:179], v[44:47]
	v_mfma_f32_16x16x32_bf16 v[40:43], v[68:71], v[176:179], v[40:43]
	v_mfma_f32_16x16x32_bf16 v[28:31], v[60:63], v[194:197], v[28:31]
	v_mfma_f32_16x16x32_bf16 v[24:27], v[68:71], v[194:197], v[24:27]
	v_mfma_f32_16x16x32_bf16 v[12:15], v[60:63], v[202:205], v[12:15]
	v_mfma_f32_16x16x32_bf16 v[8:11], v[68:71], v[202:205], v[8:11]
	v_mfma_f32_16x16x32_bf16 v[52:55], v[144:147], v[160:163], v[52:55]
	v_mfma_f32_16x16x32_bf16 v[48:51], v[152:155], v[160:163], v[48:51]
	v_mfma_f32_16x16x32_bf16 v[36:39], v[144:147], v[168:171], v[36:39]
	v_mfma_f32_16x16x32_bf16 v[32:35], v[152:155], v[168:171], v[32:35]
	v_mfma_f32_16x16x32_bf16 v[20:23], v[144:147], v[190:193], v[20:23]
	v_mfma_f32_16x16x32_bf16 v[16:19], v[152:155], v[190:193], v[16:19]
	v_mfma_f32_16x16x32_bf16 v[4:7], v[144:147], v[198:201], v[4:7]
	v_mfma_f32_16x16x32_bf16 v[0:3], v[152:155], v[198:201], v[0:3]
	v_mfma_f32_16x16x32_bf16 v[52:55], v[148:151], v[164:167], v[52:55]
	v_mfma_f32_16x16x32_bf16 v[48:51], v[156:159], v[164:167], v[48:51]
	v_mfma_f32_16x16x32_bf16 v[36:39], v[148:151], v[176:179], v[36:39]
	v_mfma_f32_16x16x32_bf16 v[32:35], v[156:159], v[176:179], v[32:35]
	v_mfma_f32_16x16x32_bf16 v[20:23], v[148:151], v[194:197], v[20:23]
	v_mfma_f32_16x16x32_bf16 v[16:19], v[156:159], v[194:197], v[16:19]
	v_mfma_f32_16x16x32_bf16 v[4:7], v[148:151], v[202:205], v[4:7]
	v_mfma_f32_16x16x32_bf16 v[0:3], v[156:159], v[202:205], v[0:3]
	s_setprio 0
	s_barrier
	s_add_i32 s79, 0, 0x18000
	s_add_i32 s93, 0, 0x1c000
	v_add_u32_e32 v68, s79, v218
	v_add_u32_e32 v156, s93, v218
	ds_read_b128 v[56:59], v68
	ds_read_b128 v[60:63], v68 offset:1024
	ds_read_b128 v[64:67], v68 offset:2048
	ds_read_b128 v[68:71], v68 offset:3072
	ds_read_b128 v[144:147], v156
	ds_read_b128 v[148:151], v156 offset:1024
	ds_read_b128 v[152:155], v156 offset:2048
	ds_read_b128 v[156:159], v156 offset:3072
	s_add_u32 s38, s38, s50
	s_addc_u32 s39, s39, 0
	s_mov_b32 m0, s68
	v_lshl_add_u64 v[228:229], s[38:39], 0, v[184:185]
	ds_read_b128 v[160:163], v220 offset:32768
	ds_read_b128 v[164:167], v220 offset:33792
	ds_read_b128 v[168:171], v220 offset:34816
	ds_read_b128 v[176:179], v220 offset:35840
	ds_read_b128 v[190:193], v220 offset:36864
	ds_read_b128 v[194:197], v220 offset:37888
	ds_read_b128 v[198:201], v220 offset:38912
	ds_read_b128 v[202:205], v220 offset:39936
	global_load_lds_dwordx4 v[228:229], off
	v_lshl_add_u64 v[228:229], s[38:39], 0, v[182:183]
	s_mov_b32 m0, s69
	s_nop 0
	global_load_lds_dwordx4 v[228:229], off
	s_waitcnt vmcnt(8)
	s_waitcnt lgkmcnt(0)
	s_barrier
	s_setprio 1
	s_waitcnt lgkmcnt(0)
	v_mfma_f32_16x16x32_bf16 v[140:143], v[56:59], v[160:163], v[140:143]
	v_mfma_f32_16x16x32_bf16 v[136:139], v[64:67], v[160:163], v[136:139]
	v_mfma_f32_16x16x32_bf16 v[124:127], v[56:59], v[168:171], v[124:127]
	v_mfma_f32_16x16x32_bf16 v[120:123], v[64:67], v[168:171], v[120:123]
	v_mfma_f32_16x16x32_bf16 v[108:111], v[56:59], v[190:193], v[108:111]
	v_mfma_f32_16x16x32_bf16 v[104:107], v[64:67], v[190:193], v[104:107]
	v_mfma_f32_16x16x32_bf16 v[92:95], v[56:59], v[198:201], v[92:95]
	v_mfma_f32_16x16x32_bf16 v[88:91], v[64:67], v[198:201], v[88:91]
	v_mfma_f32_16x16x32_bf16 v[140:143], v[60:63], v[164:167], v[140:143]
	v_mfma_f32_16x16x32_bf16 v[136:139], v[68:71], v[164:167], v[136:139]
	v_mfma_f32_16x16x32_bf16 v[124:127], v[60:63], v[176:179], v[124:127]
	v_mfma_f32_16x16x32_bf16 v[120:123], v[68:71], v[176:179], v[120:123]
	v_mfma_f32_16x16x32_bf16 v[108:111], v[60:63], v[194:197], v[108:111]
	v_mfma_f32_16x16x32_bf16 v[104:107], v[68:71], v[194:197], v[104:107]
	v_mfma_f32_16x16x32_bf16 v[92:95], v[60:63], v[202:205], v[92:95]
	v_mfma_f32_16x16x32_bf16 v[88:91], v[68:71], v[202:205], v[88:91]
	v_mfma_f32_16x16x32_bf16 v[132:135], v[144:147], v[160:163], v[132:135]
	v_mfma_f32_16x16x32_bf16 v[128:131], v[152:155], v[160:163], v[128:131]
	v_mfma_f32_16x16x32_bf16 v[116:119], v[144:147], v[168:171], v[116:119]
	v_mfma_f32_16x16x32_bf16 v[112:115], v[152:155], v[168:171], v[112:115]
	v_mfma_f32_16x16x32_bf16 v[100:103], v[144:147], v[190:193], v[100:103]
	v_mfma_f32_16x16x32_bf16 v[96:99], v[152:155], v[190:193], v[96:99]
	v_mfma_f32_16x16x32_bf16 v[84:87], v[144:147], v[198:201], v[84:87]
	v_mfma_f32_16x16x32_bf16 v[80:83], v[152:155], v[198:201], v[80:83]
	v_mfma_f32_16x16x32_bf16 v[132:135], v[148:151], v[164:167], v[132:135]
	v_mfma_f32_16x16x32_bf16 v[128:131], v[156:159], v[164:167], v[128:131]
	v_mfma_f32_16x16x32_bf16 v[116:119], v[148:151], v[176:179], v[116:119]
	v_mfma_f32_16x16x32_bf16 v[112:115], v[156:159], v[176:179], v[112:115]
	v_mfma_f32_16x16x32_bf16 v[100:103], v[148:151], v[194:197], v[100:103]
	v_mfma_f32_16x16x32_bf16 v[96:99], v[156:159], v[194:197], v[96:99]
	v_mfma_f32_16x16x32_bf16 v[84:87], v[148:151], v[202:205], v[84:87]
	v_mfma_f32_16x16x32_bf16 v[80:83], v[156:159], v[202:205], v[80:83]
	s_setprio 0
	s_barrier
; #define PG8_STAGE(bufoff, gbase, voff) do { _Pragma("unroll") for (int _i = 0; _i < 2; ++_i) \
;         __builtin_amdgcn_global_load_lds((const unsigned*)((const char*)(gbase) + (voff)[_i]), (PG8_LAS unsigned*)(lds + (bufoff) + ldsw + _i * 8192), 16, 0, 0); } while (0)
; #define PG8_LDA(dst, b, h) do { _Pragma("unroll") for (int m = 0; m < 4; ++m) _Pragma("unroll") for (int k = 0; k < 2; ++k) dst[m][k] = *(const PG8_LAS bf16x8*)(lds + PG8_SA(b, h) + aoff + m * 2048 + k * 1024); } while (0)
; #define PG8_MMA(ai, bj, At, Bt) do { __builtin_amdgcn_s_setprio(1); _Pragma("unroll") for (int m = 0; m < 4; ++m) _Pragma("unroll") for (int n = 0; n < 2; ++n) _Pragma("unroll") for (int k = 0; k < 2; ++k) \
;         acc[ai][bj][m][n] = __builtin_amdgcn_mfma_f32_16x16x32_bf16(Bt[n][k], At[m][k], acc[ai][bj][m][n], 0, 0, 0); __builtin_amdgcn_s_setprio(0); } while (0)
; #define PG8_WAIT_V(n) asm volatile("s_waitcnt vmcnt(" #n ")" ::: "memory")
; #define PG8_WAIT_L(n) asm volatile("s_waitcnt lgkmcnt(" #n ")" ::: "memory")
; #define PG8_BAR __builtin_amdgcn_s_barrier()
; #define PG8_SCHED __builtin_amdgcn_sched_barrier(0)
; template <class Epi, class Sched, bool ALIGN_EPI = false, bool SP2 = false>
; __device__ __forceinline__ void gemm_phase(PG8_LAS unsigned char* lds, const Gemm g, const Sched& S, const Epi& E) {
;     ...
;             PG8_LDA(At, 1, 1); PG8_STAGE(PG8_SB(1, 0), b3, voffB); PG8_STAGE(PG8_SB(1, 1), b3 + hstep, voffB); PG8_STAGE(PG8_SA(1, 0), a3, voffA);
;             PG8_WAIT_V(8); PG8_WAIT_L(0); PG8_BAR; PG8_MMA(1, 0, At, B0); PG8_MMA(1, 1, At, B1); PG8_BAR; PG8_SCHED;
;     ...
;         if constexpr (ALIGN_EPI) { if (wr == 0) PG8_BAR; }
	s_add_i32 s38, s79, s8
	v_lshl_add_u64 v[172:173], v[172:173], 0, s[4:5]
	s_mov_b32 m0, s38
	ds_read_b128 v[160:163], v220 offset:49152
	ds_read_b128 v[164:167], v220 offset:50176
	ds_read_b128 v[168:171], v220 offset:51200
	ds_read_b128 v[176:179], v220 offset:52224
	ds_read_b128 v[190:193], v220 offset:53248
	ds_read_b128 v[194:197], v220 offset:54272
	ds_read_b128 v[198:201], v220 offset:55296
	ds_read_b128 v[202:205], v220 offset:56320
	global_load_lds_dwordx4 v[172:173], off
	v_lshl_add_u64 v[172:173], v[206:207], 0, s[4:5]
	s_add_i32 m0, s38, 0x2000
	s_add_i32 s38, s93, s8
	global_load_lds_dwordx4 v[172:173], off
	v_lshl_add_u64 v[172:173], v[208:209], 0, s[4:5]
	s_mov_b32 m0, s38
	s_nop 0
	global_load_lds_dwordx4 v[172:173], off
	v_lshl_add_u64 v[172:173], v[222:223], 0, s[4:5]
	s_add_i32 m0, s38, 0x2000
	s_nop 0
	global_load_lds_dwordx4 v[172:173], off
	v_lshl_add_u64 v[172:173], v[224:225], 0, s[4:5]
	s_mov_b32 m0, s73
	s_nop 0
	global_load_lds_dwordx4 v[172:173], off
	v_lshl_add_u64 v[172:173], v[226:227], 0, s[4:5]
	s_mov_b32 m0, s74
	s_nop 0
	global_load_lds_dwordx4 v[172:173], off
	s_waitcnt vmcnt(8)
	s_waitcnt lgkmcnt(0)
	s_barrier
	s_setprio 1
	s_waitcnt lgkmcnt(0)
	v_mfma_f32_16x16x32_bf16 v[76:79], v[56:59], v[160:163], v[76:79]
	v_mfma_f32_16x16x32_bf16 v[72:75], v[64:67], v[160:163], v[72:75]
	v_mfma_f32_16x16x32_bf16 v[44:47], v[56:59], v[168:171], v[44:47]
	v_mfma_f32_16x16x32_bf16 v[40:43], v[64:67], v[168:171], v[40:43]
	v_mfma_f32_16x16x32_bf16 v[28:31], v[56:59], v[190:193], v[28:31]
	v_mfma_f32_16x16x32_bf16 v[24:27], v[64:67], v[190:193], v[24:27]
	v_mfma_f32_16x16x32_bf16 v[12:15], v[56:59], v[198:201], v[12:15]
	v_mfma_f32_16x16x32_bf16 v[8:11], v[64:67], v[198:201], v[8:11]
	v_mfma_f32_16x16x32_bf16 v[76:79], v[60:63], v[164:167], v[76:79]
	v_mfma_f32_16x16x32_bf16 v[72:75], v[68:71], v[164:167], v[72:75]
	v_mfma_f32_16x16x32_bf16 v[44:47], v[60:63], v[176:179], v[44:47]
	v_mfma_f32_16x16x32_bf16 v[40:43], v[68:71], v[176:179], v[40:43]
	v_mfma_f32_16x16x32_bf16 v[28:31], v[60:63], v[194:197], v[28:31]
	v_mfma_f32_16x16x32_bf16 v[24:27], v[68:71], v[194:197], v[24:27]
	v_mfma_f32_16x16x32_bf16 v[12:15], v[60:63], v[202:205], v[12:15]
	v_mfma_f32_16x16x32_bf16 v[8:11], v[68:71], v[202:205], v[8:11]
	v_mfma_f32_16x16x32_bf16 v[52:55], v[144:147], v[160:163], v[52:55]
	v_mfma_f32_16x16x32_bf16 v[48:51], v[152:155], v[160:163], v[48:51]
	v_mfma_f32_16x16x32_bf16 v[36:39], v[144:147], v[168:171], v[36:39]
	v_mfma_f32_16x16x32_bf16 v[32:35], v[152:155], v[168:171], v[32:35]
	v_mfma_f32_16x16x32_bf16 v[20:23], v[144:147], v[190:193], v[20:23]
	v_mfma_f32_16x16x32_bf16 v[16:19], v[152:155], v[190:193], v[16:19]
	v_mfma_f32_16x16x32_bf16 v[4:7], v[144:147], v[198:201], v[4:7]
	v_mfma_f32_16x16x32_bf16 v[0:3], v[152:155], v[198:201], v[0:3]
	v_mfma_f32_16x16x32_bf16 v[52:55], v[148:151], v[164:167], v[52:55]
	v_mfma_f32_16x16x32_bf16 v[48:51], v[156:159], v[164:167], v[48:51]
	v_mfma_f32_16x16x32_bf16 v[36:39], v[148:151], v[176:179], v[36:39]
	v_mfma_f32_16x16x32_bf16 v[32:35], v[156:159], v[176:179], v[32:35]
	v_mfma_f32_16x16x32_bf16 v[20:23], v[148:151], v[194:197], v[20:23]
	v_mfma_f32_16x16x32_bf16 v[16:19], v[156:159], v[194:197], v[16:19]
	v_mfma_f32_16x16x32_bf16 v[4:7], v[148:151], v[202:205], v[4:7]
	v_mfma_f32_16x16x32_bf16 v[0:3], v[156:159], v[202:205], v[0:3]
	s_setprio 0
	s_barrier
	s_add_u32 s0, s0, 0x100
	s_addc_u32 s1, s1, 0
	s_add_u32 s44, s44, 0x100
	s_addc_u32 s45, s45, 0
	s_cmp_ge_u32 s78, s72
	s_mov_b32 s38, s78
	s_cbranch_scc0 .LBB0_1641
	s_and_b64 vcc, exec, s[58:59]
	s_cbranch_vccz .LBB0_1644
	s_barrier

; #define PG8_STAGE(bufoff, gbase, voff) do { _Pragma("unroll") for (int _i = 0; _i < 2; ++_i) \
;         __builtin_amdgcn_global_load_lds((const unsigned*)((const char*)(gbase) + (voff)[_i]), (PG8_LAS unsigned*)(lds + (bufoff) + ldsw + _i * 8192), 16, 0, 0); } while (0)
; #define PG8_LDA(dst, b, h) do { _Pragma("unroll") for (int m = 0; m < 4; ++m) _Pragma("unroll") for (int k = 0; k < 2; ++k) dst[m][k] = *(const PG8_LAS bf16x8*)(lds + PG8_SA(b, h) + aoff + m * 2048 + k * 1024); } while (0)
; #define PG8_LDB(dst, b, h) do { _Pragma("unroll") for (int n = 0; n < 2; ++n) _Pragma("unroll") for (int k = 0; k < 2; ++k) dst[n][k] = *(const PG8_LAS bf16x8*)(lds + PG8_SB(b, h) + boff + n * 2048 + k * 1024); } while (0)
; #define PG8_MMA(ai, bj, At, Bt) do { __builtin_amdgcn_s_setprio(1); _Pragma("unroll") for (int m = 0; m < 4; ++m) _Pragma("unroll") for (int n = 0; n < 2; ++n) _Pragma("unroll") for (int k = 0; k < 2; ++k) \
;         acc[ai][bj][m][n] = __builtin_amdgcn_mfma_f32_16x16x32_bf16(Bt[n][k], At[m][k], acc[ai][bj][m][n], 0, 0, 0); __builtin_amdgcn_s_setprio(0); } while (0)
; #define PG8_WAIT_V(n) asm volatile("s_waitcnt vmcnt(" #n ")" ::: "memory")
; #define PG8_WAIT_L(n) asm volatile("s_waitcnt lgkmcnt(" #n ")" ::: "memory")
; template <class Epi, class Sched, bool ALIGN_EPI = false, bool SP2 = false>
; __device__ __forceinline__ void gemm_phase(PG8_LAS unsigned char* lds, const Gemm g, const Sched& S, const Epi& E) {
;     ...
;             const bool last = (t == nt - 2);
;             const char* a1 = cA + (size_t)(t + 1) * kstep;
;             const char* a2 = last ? nA : cA + (size_t)(t + 2) * kstep; const char* b2 = last ? nB : cB + (size_t)(t + 2) * kstep;
;             const char* a3 = a2 + kstep; const char* b3 = b2 + kstep;
;             if (last && has_next) S.a_ready(nxt);
;             if constexpr (SP2) {
;             PG8_LDB(B0, 0, 0); PG8_LDB(B1, 0, 1); PG8_SCHED; PG8_LDA(At, 0, 0); PG8_STAGE(PG8_SA(1, 1), a1 + hstep, voffA);
;             PG8_WAIT_V(8); PG8_WAIT_L(0); PG8_BAR; PG8_MMA(0, 0, At, B0); PG8_MMA(0, 1, At, B1); PG8_BAR; PG8_SCHED;
;             PG8_LDA(At, 0, 1); PG8_STAGE(PG8_SB(0, 0), b2, voffB); PG8_STAGE(PG8_SB(0, 1), b2 + hstep, voffB); PG8_STAGE(PG8_SA(0, 0), a2, voffA);
;             PG8_WAIT_V(8); PG8_WAIT_L(0); PG8_BAR; PG8_MMA(1, 0, At, B0); PG8_MMA(1, 1, At, B1); PG8_BAR; PG8_SCHED;
.LBB0_1752:
	s_add_u32 s38, s0, 0xfffc0080
	s_addc_u32 s39, s1, -1
	s_add_i32 s74, 0, 0x10000
	s_cmp_eq_u32 s73, 12
	s_cselect_b32 s57, s51, s39
	s_cselect_b32 s56, s69, s38
	v_add_u32_e32 v151, s74, v147
	s_cselect_b32 s39, s49, s72
	s_cselect_b32 s38, s70, s71
	s_add_i32 s76, 0, 0x14000
	ds_read_b128 v[138:141], v151
	ds_read_b128 v[142:145], v151 offset:1024
	ds_read_b128 v[152:155], v151 offset:2048
	ds_read_b128 v[156:159], v151 offset:3072
	v_add_u32_e32 v151, s76, v147
	ds_read_b128 v[160:163], v151
	ds_read_b128 v[164:167], v151 offset:1024
	ds_read_b128 v[168:171], v151 offset:2048
	ds_read_b128 v[176:179], v151 offset:3072
	v_lshl_add_u64 v[172:173], s[0:1], 0, v[134:135]
	s_add_i32 m0, s58, 0xc000
	ds_read_b128 v[180:183], v150
	ds_read_b128 v[184:187], v150 offset:1024
	ds_read_b128 v[188:191], v150 offset:2048
	ds_read_b128 v[192:195], v150 offset:3072
	ds_read_b128 v[196:199], v150 offset:4096
	ds_read_b128 v[200:203], v150 offset:5120
	ds_read_b128 v[204:207], v150 offset:6144
	ds_read_b128 v[218:221], v150 offset:7168
	global_load_lds_dwordx4 v[172:173], off
	v_lshl_add_u64 v[172:173], s[0:1], 0, v[136:137]
	s_add_i32 m0, s58, 0xe000
	s_nop 0
	global_load_lds_dwordx4 v[172:173], off
	s_waitcnt vmcnt(8)
	s_waitcnt lgkmcnt(0)
	s_barrier
	s_setprio 1
	s_waitcnt lgkmcnt(0)
	v_mfma_f32_16x16x32_bf16 v[124:127], v[138:141], v[180:183], v[124:127]
	v_mfma_f32_16x16x32_bf16 v[120:123], v[152:155], v[180:183], v[120:123]
	v_mfma_f32_16x16x32_bf16 v[108:111], v[138:141], v[188:191], v[108:111]
	v_mfma_f32_16x16x32_bf16 v[104:107], v[152:155], v[188:191], v[104:107]
	v_mfma_f32_16x16x32_bf16 v[92:95], v[138:141], v[196:199], v[92:95]
	v_mfma_f32_16x16x32_bf16 v[88:91], v[152:155], v[196:199], v[88:91]
	v_mfma_f32_16x16x32_bf16 v[76:79], v[138:141], v[204:207], v[76:79]
	v_mfma_f32_16x16x32_bf16 v[72:75], v[152:155], v[204:207], v[72:75]
	v_mfma_f32_16x16x32_bf16 v[124:127], v[142:145], v[184:187], v[124:127]
	v_mfma_f32_16x16x32_bf16 v[120:123], v[156:159], v[184:187], v[120:123]
	v_mfma_f32_16x16x32_bf16 v[108:111], v[142:145], v[192:195], v[108:111]
	v_mfma_f32_16x16x32_bf16 v[104:107], v[156:159], v[192:195], v[104:107]
	v_mfma_f32_16x16x32_bf16 v[92:95], v[142:145], v[200:203], v[92:95]
	v_mfma_f32_16x16x32_bf16 v[88:91], v[156:159], v[200:203], v[88:91]
	v_mfma_f32_16x16x32_bf16 v[76:79], v[142:145], v[218:221], v[76:79]
	v_mfma_f32_16x16x32_bf16 v[72:75], v[156:159], v[218:221], v[72:75]
	v_mfma_f32_16x16x32_bf16 v[116:119], v[160:163], v[180:183], v[116:119]
	v_mfma_f32_16x16x32_bf16 v[112:115], v[168:171], v[180:183], v[112:115]
	v_mfma_f32_16x16x32_bf16 v[100:103], v[160:163], v[188:191], v[100:103]
	v_mfma_f32_16x16x32_bf16 v[96:99], v[168:171], v[188:191], v[96:99]
	v_mfma_f32_16x16x32_bf16 v[84:87], v[160:163], v[196:199], v[84:87]
	v_mfma_f32_16x16x32_bf16 v[80:83], v[168:171], v[196:199], v[80:83]
	v_mfma_f32_16x16x32_bf16 v[68:71], v[160:163], v[204:207], v[68:71]
	v_mfma_f32_16x16x32_bf16 v[64:67], v[168:171], v[204:207], v[64:67]
	v_mfma_f32_16x16x32_bf16 v[116:119], v[164:167], v[184:187], v[116:119]
	v_mfma_f32_16x16x32_bf16 v[112:115], v[176:179], v[184:187], v[112:115]
	v_mfma_f32_16x16x32_bf16 v[100:103], v[164:167], v[192:195], v[100:103]
	v_mfma_f32_16x16x32_bf16 v[96:99], v[176:179], v[192:195], v[96:99]
	v_mfma_f32_16x16x32_bf16 v[84:87], v[164:167], v[200:203], v[84:87]
	v_mfma_f32_16x16x32_bf16 v[80:83], v[176:179], v[200:203], v[80:83]
	v_mfma_f32_16x16x32_bf16 v[68:71], v[164:167], v[218:221], v[68:71]
	v_mfma_f32_16x16x32_bf16 v[64:67], v[176:179], v[218:221], v[64:67]
	s_setprio 0
	s_barrier
	s_add_i32 s74, s74, s8
	v_lshl_add_u64 v[172:173], s[38:39], 0, v[174:175]
	s_mov_b32 m0, s74
	ds_read_b128 v[180:183], v150 offset:16384
	ds_read_b128 v[184:187], v150 offset:17408
	ds_read_b128 v[188:191], v150 offset:18432
	ds_read_b128 v[192:195], v150 offset:19456
	ds_read_b128 v[196:199], v150 offset:20480
	ds_read_b128 v[200:203], v150 offset:21504
	ds_read_b128 v[204:207], v150 offset:22528
	ds_read_b128 v[218:221], v150 offset:23552
	global_load_lds_dwordx4 v[172:173], off
	s_add_i32 m0, s74, 0x2000
	s_add_u32 s74, s38, 0x40000
	v_lshl_add_u64 v[208:209], s[38:39], 0, v[128:129]
	s_addc_u32 s75, s39, 0
	s_add_i32 s76, s76, s8
	global_load_lds_dwordx4 v[208:209], off
	v_lshl_add_u64 v[222:223], s[74:75], 0, v[174:175]
	s_mov_b32 m0, s76
	v_lshl_add_u64 v[224:225], s[56:57], 0, v[130:131]
	global_load_lds_dwordx4 v[222:223], off
	v_lshl_add_u64 v[222:223], s[74:75], 0, v[128:129]
	s_add_i32 m0, s76, 0x2000
	s_nop 0
	global_load_lds_dwordx4 v[222:223], off
	v_lshl_add_u64 v[222:223], s[56:57], 0, v[132:133]
	s_mov_b32 m0, s58
	s_nop 0
	global_load_lds_dwordx4 v[222:223], off
	s_mov_b32 m0, s59
	s_nop 0
	global_load_lds_dwordx4 v[224:225], off
	s_waitcnt vmcnt(8)
	s_waitcnt lgkmcnt(0)
	s_barrier
; #define PG8_STAGE(bufoff, gbase, voff) do { _Pragma("unroll") for (int _i = 0; _i < 2; ++_i) \
;         __builtin_amdgcn_global_load_lds((const unsigned*)((const char*)(gbase) + (voff)[_i]), (PG8_LAS unsigned*)(lds + (bufoff) + ldsw + _i * 8192), 16, 0, 0); } while (0)
; #define PG8_LDA(dst, b, h) do { _Pragma("unroll") for (int m = 0; m < 4; ++m) _Pragma("unroll") for (int k = 0; k < 2; ++k) dst[m][k] = *(const PG8_LAS bf16x8*)(lds + PG8_SA(b, h) + aoff + m * 2048 + k * 1024); } while (0)
; #define PG8_LDB(dst, b, h) do { _Pragma("unroll") for (int n = 0; n < 2; ++n) _Pragma("unroll") for (int k = 0; k < 2; ++k) dst[n][k] = *(const PG8_LAS bf16x8*)(lds + PG8_SB(b, h) + boff + n * 2048 + k * 1024); } while (0)
; #define PG8_MMA(ai, bj, At, Bt) do { __builtin_amdgcn_s_setprio(1); _Pragma("unroll") for (int m = 0; m < 4; ++m) _Pragma("unroll") for (int n = 0; n < 2; ++n) _Pragma("unroll") for (int k = 0; k < 2; ++k) \
;         acc[ai][bj][m][n] = __builtin_amdgcn_mfma_f32_16x16x32_bf16(Bt[n][k], At[m][k], acc[ai][bj][m][n], 0, 0, 0); __builtin_amdgcn_s_setprio(0); } while (0)
; #define PG8_WAIT_V(n) asm volatile("s_waitcnt vmcnt(" #n ")" ::: "memory")
; #define PG8_WAIT_L(n) asm volatile("s_waitcnt lgkmcnt(" #n ")" ::: "memory")
; #define PG8_BAR __builtin_amdgcn_s_barrier()
; #define PG8_SCHED __builtin_amdgcn_sched_barrier(0)
; template <class Epi, class Sched, bool ALIGN_EPI = false, bool SP2 = false>
; __device__ __forceinline__ void gemm_phase(PG8_LAS unsigned char* lds, const Gemm g, const Sched& S, const Epi& E) {
;     ...
;             PG8_WAIT_V(8); PG8_WAIT_L(0); PG8_BAR; PG8_MMA(1, 0, At, B0); PG8_MMA(1, 1, At, B1); PG8_BAR; PG8_SCHED;
;             PG8_LDB(B0, 1, 0); PG8_LDB(B1, 1, 1); PG8_SCHED; PG8_LDA(At, 1, 0); PG8_STAGE(PG8_SA(0, 1), a2 + hstep, voffA);
;             PG8_WAIT_V(8); PG8_WAIT_L(0); PG8_BAR; PG8_MMA(0, 0, At, B0); PG8_MMA(0, 1, At, B1); PG8_BAR; PG8_SCHED;
;             PG8_LDA(At, 1, 1); PG8_STAGE(PG8_SB(1, 0), b3, voffB); PG8_STAGE(PG8_SB(1, 1), b3 + hstep, voffB); PG8_STAGE(PG8_SA(1, 0), a3, voffA);
	s_setprio 1
	s_waitcnt lgkmcnt(0)
	v_mfma_f32_16x16x32_bf16 v[60:63], v[138:141], v[180:183], v[60:63]
	v_mfma_f32_16x16x32_bf16 v[56:59], v[152:155], v[180:183], v[56:59]
	v_mfma_f32_16x16x32_bf16 v[44:47], v[138:141], v[188:191], v[44:47]
	v_mfma_f32_16x16x32_bf16 v[40:43], v[152:155], v[188:191], v[40:43]
	v_mfma_f32_16x16x32_bf16 v[28:31], v[138:141], v[196:199], v[28:31]
	v_mfma_f32_16x16x32_bf16 v[24:27], v[152:155], v[196:199], v[24:27]
	v_mfma_f32_16x16x32_bf16 v[12:15], v[138:141], v[204:207], v[12:15]
	v_mfma_f32_16x16x32_bf16 v[8:11], v[152:155], v[204:207], v[8:11]
	v_mfma_f32_16x16x32_bf16 v[60:63], v[142:145], v[184:187], v[60:63]
	v_mfma_f32_16x16x32_bf16 v[56:59], v[156:159], v[184:187], v[56:59]
	v_mfma_f32_16x16x32_bf16 v[44:47], v[142:145], v[192:195], v[44:47]
	v_mfma_f32_16x16x32_bf16 v[40:43], v[156:159], v[192:195], v[40:43]
	v_mfma_f32_16x16x32_bf16 v[28:31], v[142:145], v[200:203], v[28:31]
	v_mfma_f32_16x16x32_bf16 v[24:27], v[156:159], v[200:203], v[24:27]
	v_mfma_f32_16x16x32_bf16 v[12:15], v[142:145], v[218:221], v[12:15]
	v_mfma_f32_16x16x32_bf16 v[8:11], v[156:159], v[218:221], v[8:11]
	v_mfma_f32_16x16x32_bf16 v[52:55], v[160:163], v[180:183], v[52:55]
	v_mfma_f32_16x16x32_bf16 v[48:51], v[168:171], v[180:183], v[48:51]
	v_mfma_f32_16x16x32_bf16 v[36:39], v[160:163], v[188:191], v[36:39]
	v_mfma_f32_16x16x32_bf16 v[32:35], v[168:171], v[188:191], v[32:35]
	v_mfma_f32_16x16x32_bf16 v[20:23], v[160:163], v[196:199], v[20:23]
	v_mfma_f32_16x16x32_bf16 v[16:19], v[168:171], v[196:199], v[16:19]
	v_mfma_f32_16x16x32_bf16 v[4:7], v[160:163], v[204:207], v[4:7]
	v_mfma_f32_16x16x32_bf16 v[0:3], v[168:171], v[204:207], v[0:3]
	v_mfma_f32_16x16x32_bf16 v[52:55], v[164:167], v[184:187], v[52:55]
	v_mfma_f32_16x16x32_bf16 v[48:51], v[176:179], v[184:187], v[48:51]
	v_mfma_f32_16x16x32_bf16 v[36:39], v[164:167], v[192:195], v[36:39]
	v_mfma_f32_16x16x32_bf16 v[32:35], v[176:179], v[192:195], v[32:35]
	v_mfma_f32_16x16x32_bf16 v[20:23], v[164:167], v[200:203], v[20:23]
	v_mfma_f32_16x16x32_bf16 v[16:19], v[176:179], v[200:203], v[16:19]
	v_mfma_f32_16x16x32_bf16 v[4:7], v[164:167], v[218:221], v[4:7]
	v_mfma_f32_16x16x32_bf16 v[0:3], v[176:179], v[218:221], v[0:3]
	s_setprio 0
	s_barrier
	s_add_i32 s74, 0, 0x18000
	v_add_u32_e32 v151, s74, v147
	s_add_i32 s75, 0, 0x1c000
	ds_read_b128 v[138:141], v151
	ds_read_b128 v[142:145], v151 offset:1024
	ds_read_b128 v[152:155], v151 offset:2048
	ds_read_b128 v[156:159], v151 offset:3072
	v_add_u32_e32 v151, s75, v147
	ds_read_b128 v[160:163], v151
	ds_read_b128 v[164:167], v151 offset:1024
	ds_read_b128 v[168:171], v151 offset:2048
	ds_read_b128 v[176:179], v151 offset:3072
	s_add_u32 s56, s56, 0x40000
	s_addc_u32 s57, s57, 0
	s_mov_b32 m0, s60
	v_lshl_add_u64 v[226:227], s[56:57], 0, v[132:133]
	ds_read_b128 v[180:183], v150 offset:32768
	ds_read_b128 v[184:187], v150 offset:33792
	ds_read_b128 v[188:191], v150 offset:34816
	ds_read_b128 v[192:195], v150 offset:35840
	ds_read_b128 v[196:199], v150 offset:36864
	ds_read_b128 v[200:203], v150 offset:37888
	ds_read_b128 v[204:207], v150 offset:38912
	ds_read_b128 v[218:221], v150 offset:39936
	global_load_lds_dwordx4 v[226:227], off
	v_lshl_add_u64 v[226:227], s[56:57], 0, v[130:131]
	s_mov_b32 m0, s61
	s_nop 0
	global_load_lds_dwordx4 v[226:227], off
	s_waitcnt vmcnt(8)
	s_waitcnt lgkmcnt(0)
	s_barrier
	s_setprio 1
	s_waitcnt lgkmcnt(0)
	v_mfma_f32_16x16x32_bf16 v[124:127], v[138:141], v[180:183], v[124:127]
	v_mfma_f32_16x16x32_bf16 v[120:123], v[152:155], v[180:183], v[120:123]
	v_mfma_f32_16x16x32_bf16 v[108:111], v[138:141], v[188:191], v[108:111]
	v_mfma_f32_16x16x32_bf16 v[104:107], v[152:155], v[188:191], v[104:107]
	v_mfma_f32_16x16x32_bf16 v[92:95], v[138:141], v[196:199], v[92:95]
	v_mfma_f32_16x16x32_bf16 v[88:91], v[152:155], v[196:199], v[88:91]
	v_mfma_f32_16x16x32_bf16 v[76:79], v[138:141], v[204:207], v[76:79]
	v_mfma_f32_16x16x32_bf16 v[72:75], v[152:155], v[204:207], v[72:75]
	v_mfma_f32_16x16x32_bf16 v[124:127], v[142:145], v[184:187], v[124:127]
	v_mfma_f32_16x16x32_bf16 v[120:123], v[156:159], v[184:187], v[120:123]
	v_mfma_f32_16x16x32_bf16 v[108:111], v[142:145], v[192:195], v[108:111]
	v_mfma_f32_16x16x32_bf16 v[104:107], v[156:159], v[192:195], v[104:107]
	v_mfma_f32_16x16x32_bf16 v[92:95], v[142:145], v[200:203], v[92:95]
	v_mfma_f32_16x16x32_bf16 v[88:91], v[156:159], v[200:203], v[88:91]
	v_mfma_f32_16x16x32_bf16 v[76:79], v[142:145], v[218:221], v[76:79]
	v_mfma_f32_16x16x32_bf16 v[72:75], v[156:159], v[218:221], v[72:75]
	v_mfma_f32_16x16x32_bf16 v[116:119], v[160:163], v[180:183], v[116:119]
	v_mfma_f32_16x16x32_bf16 v[112:115], v[168:171], v[180:183], v[112:115]
	v_mfma_f32_16x16x32_bf16 v[100:103], v[160:163], v[188:191], v[100:103]
	v_mfma_f32_16x16x32_bf16 v[96:99], v[168:171], v[188:191], v[96:99]
	v_mfma_f32_16x16x32_bf16 v[84:87], v[160:163], v[196:199], v[84:87]
	v_mfma_f32_16x16x32_bf16 v[80:83], v[168:171], v[196:199], v[80:83]
	v_mfma_f32_16x16x32_bf16 v[68:71], v[160:163], v[204:207], v[68:71]
	v_mfma_f32_16x16x32_bf16 v[64:67], v[168:171], v[204:207], v[64:67]
	v_mfma_f32_16x16x32_bf16 v[116:119], v[164:167], v[184:187], v[116:119]
	v_mfma_f32_16x16x32_bf16 v[112:115], v[176:179], v[184:187], v[112:115]
	v_mfma_f32_16x16x32_bf16 v[100:103], v[164:167], v[192:195], v[100:103]
	v_mfma_f32_16x16x32_bf16 v[96:99], v[176:179], v[192:195], v[96:99]
	v_mfma_f32_16x16x32_bf16 v[84:87], v[164:167], v[200:203], v[84:87]
	v_mfma_f32_16x16x32_bf16 v[80:83], v[176:179], v[200:203], v[80:83]
	v_mfma_f32_16x16x32_bf16 v[68:71], v[164:167], v[218:221], v[68:71]
	v_mfma_f32_16x16x32_bf16 v[64:67], v[176:179], v[218:221], v[64:67]
	s_setprio 0
	s_barrier
; #define PG8_STAGE(bufoff, gbase, voff) do { _Pragma("unroll") for (int _i = 0; _i < 2; ++_i) \
;         __builtin_amdgcn_global_load_lds((const unsigned*)((const char*)(gbase) + (voff)[_i]), (PG8_LAS unsigned*)(lds + (bufoff) + ldsw + _i * 8192), 16, 0, 0); } while (0)
; #define PG8_LDA(dst, b, h) do { _Pragma("unroll") for (int m = 0; m < 4; ++m) _Pragma("unroll") for (int k = 0; k < 2; ++k) dst[m][k] = *(const PG8_LAS bf16x8*)(lds + PG8_SA(b, h) + aoff + m * 2048 + k * 1024); } while (0)
; #define PG8_MMA(ai, bj, At, Bt) do { __builtin_amdgcn_s_setprio(1); _Pragma("unroll") for (int m = 0; m < 4; ++m) _Pragma("unroll") for (int n = 0; n < 2; ++n) _Pragma("unroll") for (int k = 0; k < 2; ++k) \
;         acc[ai][bj][m][n] = __builtin_amdgcn_mfma_f32_16x16x32_bf16(Bt[n][k], At[m][k], acc[ai][bj][m][n], 0, 0, 0); __builtin_amdgcn_s_setprio(0); } while (0)
; #define PG8_WAIT_V(n) asm volatile("s_waitcnt vmcnt(" #n ")" ::: "memory")
; #define PG8_WAIT_L(n) asm volatile("s_waitcnt lgkmcnt(" #n ")" ::: "memory")
; #define PG8_BAR __builtin_amdgcn_s_barrier()
; #define PG8_SCHED __builtin_amdgcn_sched_barrier(0)
; template <class Epi, class Sched, bool ALIGN_EPI = false, bool SP2 = false>
; __device__ __forceinline__ void gemm_phase(PG8_LAS unsigned char* lds, const Gemm g, const Sched& S, const Epi& E) {
;     ...
;             PG8_LDA(At, 1, 1); PG8_STAGE(PG8_SB(1, 0), b3, voffB); PG8_STAGE(PG8_SB(1, 1), b3 + hstep, voffB); PG8_STAGE(PG8_SA(1, 0), a3, voffA);
;             PG8_WAIT_V(8); PG8_WAIT_L(0); PG8_BAR; PG8_MMA(1, 0, At, B0); PG8_MMA(1, 1, At, B1); PG8_BAR; PG8_SCHED;
;     ...
;         if constexpr (ALIGN_EPI) { if (wr == 0) PG8_BAR; }
	s_add_i32 s56, s74, s8
	v_lshl_add_u64 v[172:173], v[172:173], 0, s[4:5]
	s_mov_b32 m0, s56
	ds_read_b128 v[180:183], v150 offset:49152
	ds_read_b128 v[184:187], v150 offset:50176
	ds_read_b128 v[188:191], v150 offset:51200
	ds_read_b128 v[192:195], v150 offset:52224
	ds_read_b128 v[196:199], v150 offset:53248
	ds_read_b128 v[200:203], v150 offset:54272
	ds_read_b128 v[204:207], v150 offset:55296
	ds_read_b128 v[218:221], v150 offset:56320
	global_load_lds_dwordx4 v[172:173], off
	s_add_i32 m0, s56, 0x2000
	s_add_u32 s38, s38, 0x40080
	v_lshl_add_u64 v[172:173], v[208:209], 0, s[4:5]
	s_addc_u32 s39, s39, 0
	s_add_i32 s56, s75, s8
	global_load_lds_dwordx4 v[172:173], off
	v_lshl_add_u64 v[172:173], s[38:39], 0, v[174:175]
	s_mov_b32 m0, s56
	s_nop 0
	global_load_lds_dwordx4 v[172:173], off
	v_lshl_add_u64 v[172:173], s[38:39], 0, v[128:129]
	s_add_i32 m0, s56, 0x2000
	s_nop 0
	global_load_lds_dwordx4 v[172:173], off
	v_lshl_add_u64 v[172:173], v[222:223], 0, s[4:5]
	s_mov_b32 m0, s62
	s_nop 0
	global_load_lds_dwordx4 v[172:173], off
	v_lshl_add_u64 v[172:173], v[224:225], 0, s[4:5]
	s_mov_b32 m0, s63
	s_nop 0
	global_load_lds_dwordx4 v[172:173], off
	s_waitcnt vmcnt(8)
	s_waitcnt lgkmcnt(0)
	s_barrier
	s_setprio 1
	s_waitcnt lgkmcnt(0)
	v_mfma_f32_16x16x32_bf16 v[60:63], v[138:141], v[180:183], v[60:63]
	v_mfma_f32_16x16x32_bf16 v[56:59], v[152:155], v[180:183], v[56:59]
	v_mfma_f32_16x16x32_bf16 v[44:47], v[138:141], v[188:191], v[44:47]
	v_mfma_f32_16x16x32_bf16 v[40:43], v[152:155], v[188:191], v[40:43]
	v_mfma_f32_16x16x32_bf16 v[28:31], v[138:141], v[196:199], v[28:31]
	v_mfma_f32_16x16x32_bf16 v[24:27], v[152:155], v[196:199], v[24:27]
	v_mfma_f32_16x16x32_bf16 v[12:15], v[138:141], v[204:207], v[12:15]
	v_mfma_f32_16x16x32_bf16 v[8:11], v[152:155], v[204:207], v[8:11]
	v_mfma_f32_16x16x32_bf16 v[60:63], v[142:145], v[184:187], v[60:63]
	v_mfma_f32_16x16x32_bf16 v[56:59], v[156:159], v[184:187], v[56:59]
	v_mfma_f32_16x16x32_bf16 v[44:47], v[142:145], v[192:195], v[44:47]
	v_mfma_f32_16x16x32_bf16 v[40:43], v[156:159], v[192:195], v[40:43]
	v_mfma_f32_16x16x32_bf16 v[28:31], v[142:145], v[200:203], v[28:31]
	v_mfma_f32_16x16x32_bf16 v[24:27], v[156:159], v[200:203], v[24:27]
	v_mfma_f32_16x16x32_bf16 v[12:15], v[142:145], v[218:221], v[12:15]
	v_mfma_f32_16x16x32_bf16 v[8:11], v[156:159], v[218:221], v[8:11]
	v_mfma_f32_16x16x32_bf16 v[52:55], v[160:163], v[180:183], v[52:55]
	v_mfma_f32_16x16x32_bf16 v[48:51], v[168:171], v[180:183], v[48:51]
	v_mfma_f32_16x16x32_bf16 v[36:39], v[160:163], v[188:191], v[36:39]
	v_mfma_f32_16x16x32_bf16 v[32:35], v[168:171], v[188:191], v[32:35]
	v_mfma_f32_16x16x32_bf16 v[20:23], v[160:163], v[196:199], v[20:23]
	v_mfma_f32_16x16x32_bf16 v[16:19], v[168:171], v[196:199], v[16:19]
	v_mfma_f32_16x16x32_bf16 v[4:7], v[160:163], v[204:207], v[4:7]
	v_mfma_f32_16x16x32_bf16 v[0:3], v[168:171], v[204:207], v[0:3]
	v_mfma_f32_16x16x32_bf16 v[52:55], v[164:167], v[184:187], v[52:55]
	v_mfma_f32_16x16x32_bf16 v[48:51], v[176:179], v[184:187], v[48:51]
	v_mfma_f32_16x16x32_bf16 v[36:39], v[164:167], v[192:195], v[36:39]
	v_mfma_f32_16x16x32_bf16 v[32:35], v[176:179], v[192:195], v[32:35]
	v_mfma_f32_16x16x32_bf16 v[20:23], v[164:167], v[200:203], v[20:23]
	v_mfma_f32_16x16x32_bf16 v[16:19], v[176:179], v[200:203], v[16:19]
	v_mfma_f32_16x16x32_bf16 v[4:7], v[164:167], v[218:221], v[4:7]
	v_mfma_f32_16x16x32_bf16 v[0:3], v[176:179], v[218:221], v[0:3]
	s_setprio 0
	s_barrier
	s_add_i32 s73, s73, 2
	s_add_u32 s0, s0, 0x100
	s_addc_u32 s1, s1, 0
	s_add_u32 s71, s71, 0x100
	s_addc_u32 s72, s72, 0
	s_cmp_gt_u32 s73, 13
	s_cbranch_scc0 .LBB0_1752
	s_and_b64 vcc, exec, s[46:47]
	s_cbranch_vccz .LBB0_1755
	s_barrier

; #define PG8_STAGE(bufoff, gbase, voff) do { _Pragma("unroll") for (int _i = 0; _i < 2; ++_i) \
;         __builtin_amdgcn_global_load_lds((const unsigned*)((const char*)(gbase) + (voff)[_i]), (PG8_LAS unsigned*)(lds + (bufoff) + ldsw + _i * 8192), 16, 0, 0); } while (0)
; #define PG8_LDA(dst, b, h) do { _Pragma("unroll") for (int m = 0; m < 4; ++m) _Pragma("unroll") for (int k = 0; k < 2; ++k) dst[m][k] = *(const PG8_LAS bf16x8*)(lds + PG8_SA(b, h) + aoff + m * 2048 + k * 1024); } while (0)
; #define PG8_LDB(dst, b, h) do { _Pragma("unroll") for (int n = 0; n < 2; ++n) _Pragma("unroll") for (int k = 0; k < 2; ++k) dst[n][k] = *(const PG8_LAS bf16x8*)(lds + PG8_SB(b, h) + boff + n * 2048 + k * 1024); } while (0)
; #define PG8_MMA(ai, bj, At, Bt) do { __builtin_amdgcn_s_setprio(1); _Pragma("unroll") for (int m = 0; m < 4; ++m) _Pragma("unroll") for (int n = 0; n < 2; ++n) _Pragma("unroll") for (int k = 0; k < 2; ++k) \
;         acc[ai][bj][m][n] = __builtin_amdgcn_mfma_f32_16x16x32_bf16(Bt[n][k], At[m][k], acc[ai][bj][m][n], 0, 0, 0); __builtin_amdgcn_s_setprio(0); } while (0)
; #define PG8_WAIT_V(n) asm volatile("s_waitcnt vmcnt(" #n ")" ::: "memory")
; #define PG8_WAIT_L(n) asm volatile("s_waitcnt lgkmcnt(" #n ")" ::: "memory")
; template <class Epi, class Sched, bool ALIGN_EPI = false, bool SP2 = false>
; __device__ __forceinline__ void gemm_phase(PG8_LAS unsigned char* lds, const Gemm g, const Sched& S, const Epi& E) {
;     ...
;             const bool last = (t == nt - 2);
;             const char* a1 = cA + (size_t)(t + 1) * kstep;
;             const char* a2 = last ? nA : cA + (size_t)(t + 2) * kstep; const char* b2 = last ? nB : cB + (size_t)(t + 2) * kstep;
;             const char* a3 = a2 + kstep; const char* b3 = b2 + kstep;
;             if (last && has_next) S.a_ready(nxt);
;             if constexpr (SP2) {
;             PG8_LDB(B0, 0, 0); PG8_LDB(B1, 0, 1); PG8_SCHED; PG8_LDA(At, 0, 0); PG8_STAGE(PG8_SA(1, 1), a1 + hstep, voffA);
;             PG8_WAIT_V(8); PG8_WAIT_L(0); PG8_BAR; PG8_MMA(0, 0, At, B0); PG8_MMA(0, 1, At, B1); PG8_BAR; PG8_SCHED;
;             PG8_LDA(At, 0, 1); PG8_STAGE(PG8_SB(0, 0), b2, voffB); PG8_STAGE(PG8_SB(0, 1), b2 + hstep, voffB); PG8_STAGE(PG8_SA(0, 0), a2, voffA);
;             PG8_WAIT_V(8); PG8_WAIT_L(0); PG8_BAR; PG8_MMA(1, 0, At, B0); PG8_MMA(1, 1, At, B1); PG8_BAR; PG8_SCHED;
.LBB0_1845:
	s_add_u32 s54, s0, 0xfff00080
	s_addc_u32 s55, s1, -1
	s_add_i32 s74, 0, 0x10000
	s_cmp_eq_u32 s73, 60
	s_cselect_b32 s57, s49, s55
	s_cselect_b32 s56, s69, s54
	s_cselect_b32 s55, s47, s72
	s_cselect_b32 s54, s70, s71
	s_add_i32 s76, 0, 0x14000
	v_add_u32_e32 v140, s74, v189
	v_add_u32_e32 v166, s76, v189
	ds_read_b128 v[128:131], v140
	ds_read_b128 v[132:135], v140 offset:1024
	ds_read_b128 v[136:139], v140 offset:2048
	ds_read_b128 v[140:143], v140 offset:3072
	ds_read_b128 v[144:147], v166
	ds_read_b128 v[148:151], v166 offset:1024
	ds_read_b128 v[162:165], v166 offset:2048
	ds_read_b128 v[166:169], v166 offset:3072
	v_lshl_add_u64 v[208:209], s[0:1], 0, v[158:159]
	s_add_i32 m0, s59, 0xc000
	ds_read_b128 v[170:173], v191
	ds_read_b128 v[176:179], v191 offset:1024
	ds_read_b128 v[180:183], v191 offset:2048
	ds_read_b128 v[184:187], v191 offset:3072
	ds_read_b128 v[192:195], v191 offset:4096
	ds_read_b128 v[196:199], v191 offset:5120
	ds_read_b128 v[200:203], v191 offset:6144
	ds_read_b128 v[204:207], v191 offset:7168
	global_load_lds_dwordx4 v[208:209], off
	v_lshl_add_u64 v[208:209], s[0:1], 0, v[160:161]
	s_add_i32 m0, s59, 0xe000
	s_nop 0
	global_load_lds_dwordx4 v[208:209], off
	s_waitcnt vmcnt(8)
	s_waitcnt lgkmcnt(0)
	s_barrier
	s_setprio 1
	s_waitcnt lgkmcnt(0)
	v_mfma_f32_16x16x32_bf16 v[124:127], v[128:131], v[170:173], v[124:127]
	v_mfma_f32_16x16x32_bf16 v[120:123], v[136:139], v[170:173], v[120:123]
	v_mfma_f32_16x16x32_bf16 v[108:111], v[128:131], v[180:183], v[108:111]
	v_mfma_f32_16x16x32_bf16 v[104:107], v[136:139], v[180:183], v[104:107]
	v_mfma_f32_16x16x32_bf16 v[92:95], v[128:131], v[192:195], v[92:95]
	v_mfma_f32_16x16x32_bf16 v[88:91], v[136:139], v[192:195], v[88:91]
	v_mfma_f32_16x16x32_bf16 v[76:79], v[128:131], v[200:203], v[76:79]
	v_mfma_f32_16x16x32_bf16 v[72:75], v[136:139], v[200:203], v[72:75]
	v_mfma_f32_16x16x32_bf16 v[124:127], v[132:135], v[176:179], v[124:127]
	v_mfma_f32_16x16x32_bf16 v[120:123], v[140:143], v[176:179], v[120:123]
	v_mfma_f32_16x16x32_bf16 v[108:111], v[132:135], v[184:187], v[108:111]
	v_mfma_f32_16x16x32_bf16 v[104:107], v[140:143], v[184:187], v[104:107]
	v_mfma_f32_16x16x32_bf16 v[92:95], v[132:135], v[196:199], v[92:95]
	v_mfma_f32_16x16x32_bf16 v[88:91], v[140:143], v[196:199], v[88:91]
	v_mfma_f32_16x16x32_bf16 v[76:79], v[132:135], v[204:207], v[76:79]
	v_mfma_f32_16x16x32_bf16 v[72:75], v[140:143], v[204:207], v[72:75]
	v_mfma_f32_16x16x32_bf16 v[116:119], v[144:147], v[170:173], v[116:119]
	v_mfma_f32_16x16x32_bf16 v[112:115], v[162:165], v[170:173], v[112:115]
	v_mfma_f32_16x16x32_bf16 v[100:103], v[144:147], v[180:183], v[100:103]
	v_mfma_f32_16x16x32_bf16 v[96:99], v[162:165], v[180:183], v[96:99]
	v_mfma_f32_16x16x32_bf16 v[84:87], v[144:147], v[192:195], v[84:87]
	v_mfma_f32_16x16x32_bf16 v[80:83], v[162:165], v[192:195], v[80:83]
	v_mfma_f32_16x16x32_bf16 v[68:71], v[144:147], v[200:203], v[68:71]
	v_mfma_f32_16x16x32_bf16 v[64:67], v[162:165], v[200:203], v[64:67]
	v_mfma_f32_16x16x32_bf16 v[116:119], v[148:151], v[176:179], v[116:119]
	v_mfma_f32_16x16x32_bf16 v[112:115], v[166:169], v[176:179], v[112:115]
	v_mfma_f32_16x16x32_bf16 v[100:103], v[148:151], v[184:187], v[100:103]
	v_mfma_f32_16x16x32_bf16 v[96:99], v[166:169], v[184:187], v[96:99]
	v_mfma_f32_16x16x32_bf16 v[84:87], v[148:151], v[196:199], v[84:87]
	v_mfma_f32_16x16x32_bf16 v[80:83], v[166:169], v[196:199], v[80:83]
	v_mfma_f32_16x16x32_bf16 v[68:71], v[148:151], v[204:207], v[68:71]
	v_mfma_f32_16x16x32_bf16 v[64:67], v[166:169], v[204:207], v[64:67]
	s_setprio 0
	s_barrier
	s_add_i32 s74, s74, s58
	v_lshl_add_u64 v[208:209], s[54:55], 0, v[174:175]
	s_mov_b32 m0, s74
	ds_read_b128 v[170:173], v191 offset:16384
	ds_read_b128 v[176:179], v191 offset:17408
	ds_read_b128 v[180:183], v191 offset:18432
	ds_read_b128 v[184:187], v191 offset:19456
	ds_read_b128 v[192:195], v191 offset:20480
	ds_read_b128 v[196:199], v191 offset:21504
	ds_read_b128 v[200:203], v191 offset:22528
	ds_read_b128 v[204:207], v191 offset:23552
	global_load_lds_dwordx4 v[208:209], off
	s_add_i32 m0, s74, 0x2000
	s_add_u32 s74, s54, 0x100000
	v_lshl_add_u64 v[218:219], s[54:55], 0, v[152:153]
	s_addc_u32 s75, s55, 0
	s_add_i32 s76, s76, s58
	global_load_lds_dwordx4 v[218:219], off
	v_lshl_add_u64 v[220:221], s[74:75], 0, v[174:175]
	s_mov_b32 m0, s76
	v_lshl_add_u64 v[222:223], s[56:57], 0, v[154:155]
	global_load_lds_dwordx4 v[220:221], off
	v_lshl_add_u64 v[220:221], s[74:75], 0, v[152:153]
	s_add_i32 m0, s76, 0x2000
	s_nop 0
	global_load_lds_dwordx4 v[220:221], off
	v_lshl_add_u64 v[220:221], s[56:57], 0, v[156:157]
	s_mov_b32 m0, s59
	s_nop 0
	global_load_lds_dwordx4 v[220:221], off
	s_mov_b32 m0, s60
	s_nop 0
	global_load_lds_dwordx4 v[222:223], off
	s_waitcnt vmcnt(8)
	s_waitcnt lgkmcnt(0)
	s_barrier
; #define PG8_STAGE(bufoff, gbase, voff) do { _Pragma("unroll") for (int _i = 0; _i < 2; ++_i) \
;         __builtin_amdgcn_global_load_lds((const unsigned*)((const char*)(gbase) + (voff)[_i]), (PG8_LAS unsigned*)(lds + (bufoff) + ldsw + _i * 8192), 16, 0, 0); } while (0)
; #define PG8_LDA(dst, b, h) do { _Pragma("unroll") for (int m = 0; m < 4; ++m) _Pragma("unroll") for (int k = 0; k < 2; ++k) dst[m][k] = *(const PG8_LAS bf16x8*)(lds + PG8_SA(b, h) + aoff + m * 2048 + k * 1024); } while (0)
; #define PG8_LDB(dst, b, h) do { _Pragma("unroll") for (int n = 0; n < 2; ++n) _Pragma("unroll") for (int k = 0; k < 2; ++k) dst[n][k] = *(const PG8_LAS bf16x8*)(lds + PG8_SB(b, h) + boff + n * 2048 + k * 1024); } while (0)
; #define PG8_MMA(ai, bj, At, Bt) do { __builtin_amdgcn_s_setprio(1); _Pragma("unroll") for (int m = 0; m < 4; ++m) _Pragma("unroll") for (int n = 0; n < 2; ++n) _Pragma("unroll") for (int k = 0; k < 2; ++k) \
;         acc[ai][bj][m][n] = __builtin_amdgcn_mfma_f32_16x16x32_bf16(Bt[n][k], At[m][k], acc[ai][bj][m][n], 0, 0, 0); __builtin_amdgcn_s_setprio(0); } while (0)
; #define PG8_WAIT_V(n) asm volatile("s_waitcnt vmcnt(" #n ")" ::: "memory")
; #define PG8_WAIT_L(n) asm volatile("s_waitcnt lgkmcnt(" #n ")" ::: "memory")
; #define PG8_BAR __builtin_amdgcn_s_barrier()
; #define PG8_SCHED __builtin_amdgcn_sched_barrier(0)
; template <class Epi, class Sched, bool ALIGN_EPI = false, bool SP2 = false>
; __device__ __forceinline__ void gemm_phase(PG8_LAS unsigned char* lds, const Gemm g, const Sched& S, const Epi& E) {
;     ...
;             PG8_WAIT_V(8); PG8_WAIT_L(0); PG8_BAR; PG8_MMA(1, 0, At, B0); PG8_MMA(1, 1, At, B1); PG8_BAR; PG8_SCHED;
;             PG8_LDB(B0, 1, 0); PG8_LDB(B1, 1, 1); PG8_SCHED; PG8_LDA(At, 1, 0); PG8_STAGE(PG8_SA(0, 1), a2 + hstep, voffA);
;             PG8_WAIT_V(8); PG8_WAIT_L(0); PG8_BAR; PG8_MMA(0, 0, At, B0); PG8_MMA(0, 1, At, B1); PG8_BAR; PG8_SCHED;
;             PG8_LDA(At, 1, 1); PG8_STAGE(PG8_SB(1, 0), b3, voffB); PG8_STAGE(PG8_SB(1, 1), b3 + hstep, voffB); PG8_STAGE(PG8_SA(1, 0), a3, voffA);
	s_setprio 1
	s_waitcnt lgkmcnt(0)
	v_mfma_f32_16x16x32_bf16 v[60:63], v[128:131], v[170:173], v[60:63]
	v_mfma_f32_16x16x32_bf16 v[56:59], v[136:139], v[170:173], v[56:59]
	v_mfma_f32_16x16x32_bf16 v[44:47], v[128:131], v[180:183], v[44:47]
	v_mfma_f32_16x16x32_bf16 v[40:43], v[136:139], v[180:183], v[40:43]
	v_mfma_f32_16x16x32_bf16 v[28:31], v[128:131], v[192:195], v[28:31]
	v_mfma_f32_16x16x32_bf16 v[24:27], v[136:139], v[192:195], v[24:27]
	v_mfma_f32_16x16x32_bf16 v[12:15], v[128:131], v[200:203], v[12:15]
	v_mfma_f32_16x16x32_bf16 v[8:11], v[136:139], v[200:203], v[8:11]
	v_mfma_f32_16x16x32_bf16 v[60:63], v[132:135], v[176:179], v[60:63]
	v_mfma_f32_16x16x32_bf16 v[56:59], v[140:143], v[176:179], v[56:59]
	v_mfma_f32_16x16x32_bf16 v[44:47], v[132:135], v[184:187], v[44:47]
	v_mfma_f32_16x16x32_bf16 v[40:43], v[140:143], v[184:187], v[40:43]
	v_mfma_f32_16x16x32_bf16 v[28:31], v[132:135], v[196:199], v[28:31]
	v_mfma_f32_16x16x32_bf16 v[24:27], v[140:143], v[196:199], v[24:27]
	v_mfma_f32_16x16x32_bf16 v[12:15], v[132:135], v[204:207], v[12:15]
	v_mfma_f32_16x16x32_bf16 v[8:11], v[140:143], v[204:207], v[8:11]
	v_mfma_f32_16x16x32_bf16 v[52:55], v[144:147], v[170:173], v[52:55]
	v_mfma_f32_16x16x32_bf16 v[48:51], v[162:165], v[170:173], v[48:51]
	v_mfma_f32_16x16x32_bf16 v[36:39], v[144:147], v[180:183], v[36:39]
	v_mfma_f32_16x16x32_bf16 v[32:35], v[162:165], v[180:183], v[32:35]
	v_mfma_f32_16x16x32_bf16 v[20:23], v[144:147], v[192:195], v[20:23]
	v_mfma_f32_16x16x32_bf16 v[16:19], v[162:165], v[192:195], v[16:19]
	v_mfma_f32_16x16x32_bf16 v[4:7], v[144:147], v[200:203], v[4:7]
	v_mfma_f32_16x16x32_bf16 v[0:3], v[162:165], v[200:203], v[0:3]
	v_mfma_f32_16x16x32_bf16 v[52:55], v[148:151], v[176:179], v[52:55]
	v_mfma_f32_16x16x32_bf16 v[48:51], v[166:169], v[176:179], v[48:51]
	v_mfma_f32_16x16x32_bf16 v[36:39], v[148:151], v[184:187], v[36:39]
	v_mfma_f32_16x16x32_bf16 v[32:35], v[166:169], v[184:187], v[32:35]
	v_mfma_f32_16x16x32_bf16 v[20:23], v[148:151], v[196:199], v[20:23]
	v_mfma_f32_16x16x32_bf16 v[16:19], v[166:169], v[196:199], v[16:19]
	v_mfma_f32_16x16x32_bf16 v[4:7], v[148:151], v[204:207], v[4:7]
	v_mfma_f32_16x16x32_bf16 v[0:3], v[166:169], v[204:207], v[0:3]
	s_setprio 0
	s_barrier
	s_add_i32 s74, 0, 0x18000
	s_add_i32 s75, 0, 0x1c000
	v_add_u32_e32 v140, s74, v189
	v_add_u32_e32 v166, s75, v189
	ds_read_b128 v[128:131], v140
	ds_read_b128 v[132:135], v140 offset:1024
	ds_read_b128 v[136:139], v140 offset:2048
	ds_read_b128 v[140:143], v140 offset:3072
	ds_read_b128 v[144:147], v166
	ds_read_b128 v[148:151], v166 offset:1024
	ds_read_b128 v[162:165], v166 offset:2048
	ds_read_b128 v[166:169], v166 offset:3072
	s_add_u32 s56, s56, 0x100000
	s_addc_u32 s57, s57, 0
	s_mov_b32 m0, s61
	v_lshl_add_u64 v[224:225], s[56:57], 0, v[156:157]
	ds_read_b128 v[170:173], v191 offset:32768
	ds_read_b128 v[176:179], v191 offset:33792
	ds_read_b128 v[180:183], v191 offset:34816
	ds_read_b128 v[184:187], v191 offset:35840
	ds_read_b128 v[192:195], v191 offset:36864
	ds_read_b128 v[196:199], v191 offset:37888
	ds_read_b128 v[200:203], v191 offset:38912
	ds_read_b128 v[204:207], v191 offset:39936
	global_load_lds_dwordx4 v[224:225], off
	v_lshl_add_u64 v[224:225], s[56:57], 0, v[154:155]
	s_mov_b32 m0, s62
	s_nop 0
	global_load_lds_dwordx4 v[224:225], off
	s_waitcnt vmcnt(8)
	s_waitcnt lgkmcnt(0)
	s_barrier
	s_setprio 1
	s_waitcnt lgkmcnt(0)
	v_mfma_f32_16x16x32_bf16 v[124:127], v[128:131], v[170:173], v[124:127]
	v_mfma_f32_16x16x32_bf16 v[120:123], v[136:139], v[170:173], v[120:123]
	v_mfma_f32_16x16x32_bf16 v[108:111], v[128:131], v[180:183], v[108:111]
	v_mfma_f32_16x16x32_bf16 v[104:107], v[136:139], v[180:183], v[104:107]
	v_mfma_f32_16x16x32_bf16 v[92:95], v[128:131], v[192:195], v[92:95]
	v_mfma_f32_16x16x32_bf16 v[88:91], v[136:139], v[192:195], v[88:91]
	v_mfma_f32_16x16x32_bf16 v[76:79], v[128:131], v[200:203], v[76:79]
	v_mfma_f32_16x16x32_bf16 v[72:75], v[136:139], v[200:203], v[72:75]
	v_mfma_f32_16x16x32_bf16 v[124:127], v[132:135], v[176:179], v[124:127]
	v_mfma_f32_16x16x32_bf16 v[120:123], v[140:143], v[176:179], v[120:123]
	v_mfma_f32_16x16x32_bf16 v[108:111], v[132:135], v[184:187], v[108:111]
	v_mfma_f32_16x16x32_bf16 v[104:107], v[140:143], v[184:187], v[104:107]
	v_mfma_f32_16x16x32_bf16 v[92:95], v[132:135], v[196:199], v[92:95]
	v_mfma_f32_16x16x32_bf16 v[88:91], v[140:143], v[196:199], v[88:91]
	v_mfma_f32_16x16x32_bf16 v[76:79], v[132:135], v[204:207], v[76:79]
	v_mfma_f32_16x16x32_bf16 v[72:75], v[140:143], v[204:207], v[72:75]
	v_mfma_f32_16x16x32_bf16 v[116:119], v[144:147], v[170:173], v[116:119]
	v_mfma_f32_16x16x32_bf16 v[112:115], v[162:165], v[170:173], v[112:115]
	v_mfma_f32_16x16x32_bf16 v[100:103], v[144:147], v[180:183], v[100:103]
	v_mfma_f32_16x16x32_bf16 v[96:99], v[162:165], v[180:183], v[96:99]
	v_mfma_f32_16x16x32_bf16 v[84:87], v[144:147], v[192:195], v[84:87]
	v_mfma_f32_16x16x32_bf16 v[80:83], v[162:165], v[192:195], v[80:83]
	v_mfma_f32_16x16x32_bf16 v[68:71], v[144:147], v[200:203], v[68:71]
	v_mfma_f32_16x16x32_bf16 v[64:67], v[162:165], v[200:203], v[64:67]
	v_mfma_f32_16x16x32_bf16 v[116:119], v[148:151], v[176:179], v[116:119]
	v_mfma_f32_16x16x32_bf16 v[112:115], v[166:169], v[176:179], v[112:115]
	v_mfma_f32_16x16x32_bf16 v[100:103], v[148:151], v[184:187], v[100:103]
	v_mfma_f32_16x16x32_bf16 v[96:99], v[166:169], v[184:187], v[96:99]
	v_mfma_f32_16x16x32_bf16 v[84:87], v[148:151], v[196:199], v[84:87]
	v_mfma_f32_16x16x32_bf16 v[80:83], v[166:169], v[196:199], v[80:83]
	v_mfma_f32_16x16x32_bf16 v[68:71], v[148:151], v[204:207], v[68:71]
	v_mfma_f32_16x16x32_bf16 v[64:67], v[166:169], v[204:207], v[64:67]
	s_setprio 0
	s_barrier
; #define PG8_STAGE(bufoff, gbase, voff) do { _Pragma("unroll") for (int _i = 0; _i < 2; ++_i) \
;         __builtin_amdgcn_global_load_lds((const unsigned*)((const char*)(gbase) + (voff)[_i]), (PG8_LAS unsigned*)(lds + (bufoff) + ldsw + _i * 8192), 16, 0, 0); } while (0)
; #define PG8_LDA(dst, b, h) do { _Pragma("unroll") for (int m = 0; m < 4; ++m) _Pragma("unroll") for (int k = 0; k < 2; ++k) dst[m][k] = *(const PG8_LAS bf16x8*)(lds + PG8_SA(b, h) + aoff + m * 2048 + k * 1024); } while (0)
; #define PG8_MMA(ai, bj, At, Bt) do { __builtin_amdgcn_s_setprio(1); _Pragma("unroll") for (int m = 0; m < 4; ++m) _Pragma("unroll") for (int n = 0; n < 2; ++n) _Pragma("unroll") for (int k = 0; k < 2; ++k) \
;         acc[ai][bj][m][n] = __builtin_amdgcn_mfma_f32_16x16x32_bf16(Bt[n][k], At[m][k], acc[ai][bj][m][n], 0, 0, 0); __builtin_amdgcn_s_setprio(0); } while (0)
; #define PG8_WAIT_V(n) asm volatile("s_waitcnt vmcnt(" #n ")" ::: "memory")
; #define PG8_WAIT_L(n) asm volatile("s_waitcnt lgkmcnt(" #n ")" ::: "memory")
; #define PG8_BAR __builtin_amdgcn_s_barrier()
; #define PG8_SCHED __builtin_amdgcn_sched_barrier(0)
; template <class Epi, class Sched, bool ALIGN_EPI = false, bool SP2 = false>
; __device__ __forceinline__ void gemm_phase(PG8_LAS unsigned char* lds, const Gemm g, const Sched& S, const Epi& E) {
;     ...
;             PG8_LDA(At, 1, 1); PG8_STAGE(PG8_SB(1, 0), b3, voffB); PG8_STAGE(PG8_SB(1, 1), b3 + hstep, voffB); PG8_STAGE(PG8_SA(1, 0), a3, voffA);
;             PG8_WAIT_V(8); PG8_WAIT_L(0); PG8_BAR; PG8_MMA(1, 0, At, B0); PG8_MMA(1, 1, At, B1); PG8_BAR; PG8_SCHED;
	s_add_i32 s56, s74, s58
	v_lshl_add_u64 v[208:209], v[208:209], 0, s[4:5]
	s_mov_b32 m0, s56
	ds_read_b128 v[170:173], v191 offset:49152
	ds_read_b128 v[176:179], v191 offset:50176
	ds_read_b128 v[180:183], v191 offset:51200
	ds_read_b128 v[184:187], v191 offset:52224
	ds_read_b128 v[192:195], v191 offset:53248
	ds_read_b128 v[196:199], v191 offset:54272
	ds_read_b128 v[200:203], v191 offset:55296
	ds_read_b128 v[204:207], v191 offset:56320
	global_load_lds_dwordx4 v[208:209], off
	s_add_i32 m0, s56, 0x2000
	s_add_u32 s54, s54, 0x100080
	v_lshl_add_u64 v[208:209], v[218:219], 0, s[4:5]
	s_addc_u32 s55, s55, 0
	s_add_i32 s56, s75, s58
	global_load_lds_dwordx4 v[208:209], off
	v_lshl_add_u64 v[208:209], s[54:55], 0, v[174:175]
	s_mov_b32 m0, s56
	s_nop 0
	global_load_lds_dwordx4 v[208:209], off
	v_lshl_add_u64 v[208:209], s[54:55], 0, v[152:153]
	s_add_i32 m0, s56, 0x2000
	s_nop 0
	global_load_lds_dwordx4 v[208:209], off
	v_lshl_add_u64 v[208:209], v[220:221], 0, s[4:5]
	s_mov_b32 m0, s64
	s_nop 0
	global_load_lds_dwordx4 v[208:209], off
	v_lshl_add_u64 v[208:209], v[222:223], 0, s[4:5]
	s_mov_b32 m0, s65
	s_nop 0
	global_load_lds_dwordx4 v[208:209], off
	s_waitcnt vmcnt(8)
	s_waitcnt lgkmcnt(0)
	s_barrier
	s_setprio 1
	s_waitcnt lgkmcnt(0)
	v_mfma_f32_16x16x32_bf16 v[60:63], v[128:131], v[170:173], v[60:63]
	v_mfma_f32_16x16x32_bf16 v[56:59], v[136:139], v[170:173], v[56:59]
	v_mfma_f32_16x16x32_bf16 v[44:47], v[128:131], v[180:183], v[44:47]
	v_mfma_f32_16x16x32_bf16 v[40:43], v[136:139], v[180:183], v[40:43]
	v_mfma_f32_16x16x32_bf16 v[28:31], v[128:131], v[192:195], v[28:31]
	v_mfma_f32_16x16x32_bf16 v[24:27], v[136:139], v[192:195], v[24:27]
	v_mfma_f32_16x16x32_bf16 v[12:15], v[128:131], v[200:203], v[12:15]
	v_mfma_f32_16x16x32_bf16 v[8:11], v[136:139], v[200:203], v[8:11]
	v_mfma_f32_16x16x32_bf16 v[60:63], v[132:135], v[176:179], v[60:63]
	v_mfma_f32_16x16x32_bf16 v[56:59], v[140:143], v[176:179], v[56:59]
	v_mfma_f32_16x16x32_bf16 v[44:47], v[132:135], v[184:187], v[44:47]
	v_mfma_f32_16x16x32_bf16 v[40:43], v[140:143], v[184:187], v[40:43]
	v_mfma_f32_16x16x32_bf16 v[28:31], v[132:135], v[196:199], v[28:31]
	v_mfma_f32_16x16x32_bf16 v[24:27], v[140:143], v[196:199], v[24:27]
	v_mfma_f32_16x16x32_bf16 v[12:15], v[132:135], v[204:207], v[12:15]
	v_mfma_f32_16x16x32_bf16 v[8:11], v[140:143], v[204:207], v[8:11]
	v_mfma_f32_16x16x32_bf16 v[52:55], v[144:147], v[170:173], v[52:55]
	v_mfma_f32_16x16x32_bf16 v[48:51], v[162:165], v[170:173], v[48:51]
	v_mfma_f32_16x16x32_bf16 v[36:39], v[144:147], v[180:183], v[36:39]
	v_mfma_f32_16x16x32_bf16 v[32:35], v[162:165], v[180:183], v[32:35]
	v_mfma_f32_16x16x32_bf16 v[20:23], v[144:147], v[192:195], v[20:23]
	v_mfma_f32_16x16x32_bf16 v[16:19], v[162:165], v[192:195], v[16:19]
	v_mfma_f32_16x16x32_bf16 v[4:7], v[144:147], v[200:203], v[4:7]
	v_mfma_f32_16x16x32_bf16 v[0:3], v[162:165], v[200:203], v[0:3]
	v_mfma_f32_16x16x32_bf16 v[52:55], v[148:151], v[176:179], v[52:55]
	v_mfma_f32_16x16x32_bf16 v[48:51], v[166:169], v[176:179], v[48:51]
	v_mfma_f32_16x16x32_bf16 v[36:39], v[148:151], v[184:187], v[36:39]
	v_mfma_f32_16x16x32_bf16 v[32:35], v[166:169], v[184:187], v[32:35]
	v_mfma_f32_16x16x32_bf16 v[20:23], v[148:151], v[196:199], v[20:23]
	v_mfma_f32_16x16x32_bf16 v[16:19], v[166:169], v[196:199], v[16:19]
	v_mfma_f32_16x16x32_bf16 v[4:7], v[148:151], v[204:207], v[4:7]
	v_mfma_f32_16x16x32_bf16 v[0:3], v[166:169], v[204:207], v[0:3]
	s_setprio 0
	s_barrier
	s_add_i32 s73, s73, 2
	s_add_u32 s0, s0, 0x100
	s_addc_u32 s1, s1, 0
	s_add_u32 s71, s71, 0x100
	s_addc_u32 s72, s72, 0
	s_cmp_gt_u32 s73, 61
	s_cbranch_scc0 .LBB0_1845
	s_and_b64 vcc, exec, s[38:39]
	s_cbranch_vccz .LBB0_1848
	s_barrier
